# RWKV scan: state carried divided by the running decay product (folded into r, a, b, k per step), renormalised every 64 steps; per-step column scaling and its LDS reads removed
# speedup vs baseline: 1.0322x; 1.0104x over previous
; __device__ __forceinline__ int tidx() { int t = threadIdx.x; asm volatile("" : "+v"(t)); return t; }
; __device__ __forceinline__ float bf2f(unsigned short b) { return __uint_as_float((unsigned)b << 16); }
; __device__ __forceinline__ f2 pfma(f2 a, f2 b, f2 c) { return __builtin_elementwise_fma(a, b, c); }
; template <bool ID> __device__ __forceinline__ void rwkv_scan(const bf16_t* __restrict__ R, const bf16_t* __restrict__ EW, const bf16_t* __restrict__ K, const bf16_t* __restrict__ V, ...
;     ...
;     { unsigned o = base; q1[0] = R[o]; q1[1] = EW[o]; q1[2] = K[o]; q1[3] = V[o]; q1[4] = A[o]; q1[5] = B[o];
;       o = base + 512u; q2[0] = R[o]; q2[1] = EW[o]; q2[2] = K[o]; q2[3] = V[o]; q2[4] = A[o]; q2[5] = B[o]; }
;     const LAS f32x4* pa = (const LAS f32x4*)L;
;     float sav, sai;
;     { L[lane] = bf2f(q1[4]);
;       f2 av = {0.f, 0.f}, ai = {0.f, 0.f};
; #pragma unroll
;       for (int q = 0; q < 16; ++q) { const f32x4 a4 = pa[q]; const f2 a01 = {a4[0], a4[1]}, a23 = {a4[2], a4[3]};
;           av = pfma(Sv[2 * q], a01, av); av = pfma(Sv[2 * q + 1], a23, av); if (ID) { ai = pfma(Si[2 * q], a01, ai); ai = pfma(Si[2 * q + 1], a23, ai); } }
;       sav = av[0] + av[1]; sai = ai[0] + ai[1]; }
; #pragma unroll 1
;     for (int s = 0; s < nsteps; ++s) {
;         L[lane] = bf2f(q2[4]); L[64 + lane] = __expf(-bf2f(q1[1])); L[128 + lane] = bf2f(q1[5]); L[192 + lane] = bf2f(q1[2]); L[256 + lane] = bf2f(q1[0]);
;         const float v = bf2f(q1[3]);
; #pragma unroll
;         for (int j = 0; j < 6; ++j) q1[j] = q2[j];
;         { const unsigned o = base + (unsigned)(s + 2 < nsteps ? s + 2 : nsteps - 1) * 512u; q2[0] = R[o]; q2[1] = EW[o]; q2[2] = K[o]; q2[3] = V[o]; q2[4] = A[o]; q2[5] = B[o]; }
; __device__ void phase_rwkv_scan(const Ctx& p, int l, LAS unsigned char* lds) {
;     ...
;             f2 Sv[32], Si[32]; const int li = tidx() & 63;
; #pragma unroll
;             for (int i = 0; i < 32; ++i) { Sv[i] = (f2){0.f, 0.f}; Si[i] = (f2){(2 * i == li) ? 1.f : 0.f, (2 * i + 1 == li) ? 1.f : 0.f}; }
;             rwkv_scan<true>(R, EW, K, V, A, B, (unsigned)((b * 8192 + c * 128) * 512 + h * 64 + lane), 128, Sv, Si, YH, QH, L, lane);
.Lscan_v:
	v_lshrrev_b32_e32 v78, 5, v139
	v_and_b32_e32 v79, 31, v139
	s_mov_b32 s26, -1
	s_mov_b32 s27, 0
	s_lshl_b32 s14, s36, 13
	s_and_b32 s14, s14, 0xffff0000
	s_lshl_b32 s15, s36, 6
	s_and_b32 s15, s15, 0x1c0
	s_or_b32 s14, s14, s15
	v_add_lshl_u32 v72, s14, v139, 1
	v_add_lshl_u32 v81, s14, v79, 1
	v_mov_b32_e32 v74, s20
	v_mov_b32_e32 v75, s21
	v_mov_b32_e32 v80, s6
	v_cndmask_b32_e64 v74, v80, v74, s[26:27]
	v_mov_b32_e32 v80, s7
	v_cndmask_b32_e64 v75, v80, v75, s[26:27]
	v_add_co_u32_e32 v74, vcc, v74, v81
	s_nop 1
	v_addc_co_u32_e32 v75, vcc, 0, v75, vcc
	v_lshl_add_u32 v76, v78, 4, s10
	v_lshl_add_u32 v77, v139, 2, s10
	v_lshl_add_u32 v251, v79, 2, s10
	v_mov_b32_e32 v246, 1.0
	v_lshlrev_b32_e32 v81, 2, v78
	v_sub_u32_e32 v81, v79, v81
	global_load_ushort v224, v72, s[4:5] offset:0
	global_load_ushort v225, v72, s[0:1] offset:0
	global_load_ushort v226, v72, s[12:13] offset:1024
	global_load_ushort v227, v[74:75], off offset:0
	global_load_ushort v228, v[74:75], off offset:64
	global_load_ushort v229, v72, s[2:3] offset:0
	global_load_ushort v230, v72, s[4:5] offset:1024
	global_load_ushort v231, v72, s[0:1] offset:1024
	global_load_ushort v232, v72, s[12:13] offset:2048
	global_load_ushort v233, v[74:75], off offset:1024
	global_load_ushort v234, v[74:75], off offset:1088
	global_load_ushort v235, v72, s[2:3] offset:1024
	global_load_ushort v82, v72, s[4:5] offset:2048
	global_load_ushort v83, v72, s[0:1] offset:2048
	global_load_ushort v84, v72, s[12:13] offset:3072
	global_load_ushort v85, v[74:75], off offset:2048
	global_load_ushort v86, v[74:75], off offset:2112
	global_load_ushort v87, v72, s[2:3] offset:2048
	v_add_u32_e32 v72, 0xc00, v72
	v_lshl_add_u64 v[74:75], v[74:75], 0, s[54:55]
	v_lshl_add_u64 v[74:75], v[74:75], 0, s[54:55]
	v_lshl_add_u64 v[74:75], v[74:75], 0, s[54:55]
	global_load_ushort v88, v72, s[4:5] offset:0
	global_load_ushort v89, v72, s[0:1] offset:0
	global_load_ushort v90, v72, s[12:13] offset:1024
	global_load_ushort v91, v[74:75], off offset:0
	global_load_ushort v92, v[74:75], off offset:64
	global_load_ushort v93, v72, s[2:3] offset:0
	v_add_u32_e32 v72, 0x400, v72
	v_lshl_add_u64 v[74:75], v[74:75], 0, s[54:55]
	v_mov_b32_e32 v0, 0
	v_mov_b32_e32 v1, 0
	v_mov_b32_e32 v2, 0
	v_mov_b32_e32 v3, 0
	v_mov_b32_e32 v4, 0
	v_mov_b32_e32 v5, 0
	v_mov_b32_e32 v6, 0
	v_mov_b32_e32 v7, 0
	v_mov_b32_e32 v8, 0
	v_mov_b32_e32 v9, 0
	v_mov_b32_e32 v10, 0
	v_mov_b32_e32 v11, 0
	v_mov_b32_e32 v12, 0
	v_mov_b32_e32 v13, 0
	v_mov_b32_e32 v14, 0
	v_mov_b32_e32 v15, 0
	v_mov_b32_e32 v16, 0
	v_mov_b32_e32 v17, 0
	v_mov_b32_e32 v18, 0
	v_mov_b32_e32 v19, 0
	v_mov_b32_e32 v20, 0
	v_mov_b32_e32 v21, 0
	v_mov_b32_e32 v22, 0
	v_mov_b32_e32 v23, 0
	v_mov_b32_e32 v24, 0
	v_mov_b32_e32 v25, 0
	v_mov_b32_e32 v26, 0
	v_mov_b32_e32 v27, 0
	v_mov_b32_e32 v28, 0
	v_mov_b32_e32 v29, 0
	v_mov_b32_e32 v30, 0
	v_mov_b32_e32 v31, 0
	v_mov_b32_e32 v32, 0
	v_mov_b32_e32 v33, 0
	v_mov_b32_e32 v34, 0
	v_mov_b32_e32 v35, 0
	v_mov_b32_e32 v36, 0
	v_mov_b32_e32 v37, 0
	v_mov_b32_e32 v38, 0
	v_mov_b32_e32 v39, 0
	v_mov_b32_e32 v40, 0
	v_mov_b32_e32 v41, 0
	v_mov_b32_e32 v42, 0
	v_mov_b32_e32 v43, 0
	v_mov_b32_e32 v44, 0
	v_mov_b32_e32 v45, 0
	v_mov_b32_e32 v46, 0
	v_mov_b32_e32 v47, 0
	v_mov_b32_e32 v48, 0
	v_mov_b32_e32 v49, 0
	v_mov_b32_e32 v50, 0
	v_mov_b32_e32 v51, 0
	v_mov_b32_e32 v52, 0
	v_mov_b32_e32 v53, 0
	v_mov_b32_e32 v54, 0
	v_mov_b32_e32 v55, 0
	v_mov_b32_e32 v56, 0
	v_mov_b32_e32 v57, 0
	v_mov_b32_e32 v58, 0
	v_mov_b32_e32 v59, 0
	v_mov_b32_e32 v60, 0
	v_mov_b32_e32 v61, 0
	v_mov_b32_e32 v62, 0
	v_mov_b32_e32 v63, 0
	s_waitcnt vmcnt(18)
	v_lshlrev_b32_e32 v78, 16, v224
	v_mul_f32_e32 v78, 0xbfb8aa3b, v78
	v_exp_f32_e32 v78, v78
	v_lshlrev_b32_e32 v79, 16, v225
	v_lshlrev_b32_e32 v80, 16, v226
	v_mul_f32_e32 v246, v246, v78
	v_mul_f32_e32 v79, v79, v246
	v_mul_f32_e32 v80, v80, v246
	v_rcp_f32_e32 v248, v246
	s_nop 0
	ds_write2st64_b32 v77, v248, v79 offset0:0 offset1:1
	ds_write_b32 v77, v80 offset:512
	ds_read_b32 v249, v251 offset:0
	ds_read_b32 v250, v251 offset:128
	v_lshlrev_b32_e32 v240, 16, v227
	v_lshlrev_b32_e32 v241, 16, v228
	s_waitcnt lgkmcnt(0)
	v_mul_f32_e32 v240, v240, v249
	v_mul_f32_e32 v241, v241, v250
	v_mov_b32_e32 v244, 0
	v_lshlrev_b32_e32 v245, 16, v229
	s_nop 0
	s_nop 0
	v_permlane32_swap_b32_e32 v244, v245
	s_movk_i32 s41, 0
; template <bool ID> __device__ __forceinline__ void rwkv_scan(const bf16_t* __restrict__ R, const bf16_t* __restrict__ EW, const bf16_t* __restrict__ K, const bf16_t* __restrict__ V, ...
;     ...
;     for (int s = 0; s < nsteps; ++s) {
;         L[lane] = bf2f(q2[4]); L[64 + lane] = __expf(-bf2f(q1[1])); L[128 + lane] = bf2f(q1[5]); L[192 + lane] = bf2f(q1[2]); L[256 + lane] = bf2f(q1[0]);
;         const float v = bf2f(q1[3]);
; #pragma unroll
;         for (int j = 0; j < 6; ++j) q1[j] = q2[j];
;         { const unsigned o = base + (unsigned)(s + 2 < nsteps ? s + 2 : nsteps - 1) * 512u; q2[0] = R[o]; q2[1] = EW[o]; q2[2] = K[o]; q2[3] = V[o]; q2[4] = A[o]; q2[5] = B[o]; }
;         const f2 sav2 = {sav, sav}, sai2 = {sai, sai}, v2 = {v, v};
;         f2 yv = {0.f, 0.f}, yi = {0.f, 0.f}, yv1 = {0.f, 0.f}, yi1 = {0.f, 0.f}, nv = {0.f, 0.f}, ni = {0.f, 0.f}, nv1 = {0.f, 0.f}, ni1 = {0.f, 0.f};
;         f32x4 ca = pa[0], cw = pa[16], cb = pa[32], ck = pa[48], cr = pa[64];
; #pragma unroll
;         for (int q = 0; q < 16; ++q) {
;             const f32x4 a4 = ca, w4 = cw, b4 = cb, k4 = ck, r4 = cr;
;             if (q < 15) { ca = pa[1 + q]; cw = pa[17 + q]; cb = pa[33 + q]; ck = pa[49 + q]; cr = pa[65 + q]; }
;             __builtin_amdgcn_sched_barrier(0);
;             { const f2 a2 = {a4[0], a4[1]}, w2 = {w4[0], w4[1]}, b2 = {b4[0], b4[1]}, k2 = {k4[0], k4[1]}, r2 = {r4[0], r4[1]};
;               f2 tv = sav2 * b2; tv = pfma(v2, k2, tv); Sv[2 * q] = pfma(Sv[2 * q], w2, tv); yv = pfma(Sv[2 * q], r2, yv); nv = pfma(Sv[2 * q], a2, nv);
;               if (ID) { const f2 ti = sai2 * b2; Si[2 * q] = pfma(Si[2 * q], w2, ti); yi = pfma(Si[2 * q], r2, yi); ni = pfma(Si[2 * q], a2, ni); } }
;             { const f2 a2 = {a4[2], a4[3]}, w2 = {w4[2], w4[3]}, b2 = {b4[2], b4[3]}, k2 = {k4[2], k4[3]}, r2 = {r4[2], r4[3]};
;               f2 tv = sav2 * b2; tv = pfma(v2, k2, tv); Sv[2 * q + 1] = pfma(Sv[2 * q + 1], w2, tv); yv1 = pfma(Sv[2 * q + 1], r2, yv1); nv1 = pfma(Sv[2 * q + 1], a2, nv1);
;               if (ID) { const f2 ti = sai2 * b2; Si[2 * q + 1] = pfma(Si[2 * q + 1], w2, ti); yi1 = pfma(Si[2 * q + 1], r2, yi1); ni1 = pfma(Si[2 * q + 1], a2, ni1); } }
;         }
;         sav = (nv[0] + nv[1]) + (nv1[0] + nv1[1]); sai = (ni[0] + ni[1]) + (ni1[0] + ni1[1]);
;         const unsigned cbo = base + (unsigned)s * 512u;
.Lscan_v_loop:
	ds_read_b128 v[192:195], v76 offset:256
	ds_read_b128 v[196:199], v76 offset:288
	ds_read_b128 v[200:203], v76 offset:320
	ds_read_b128 v[204:207], v76 offset:352
	ds_read_b128 v[208:211], v76 offset:512
	ds_read_b128 v[212:215], v76 offset:544
	ds_read_b128 v[216:219], v76 offset:576
	ds_read_b128 v[220:223], v76 offset:608
	global_load_ushort v224, v72, s[4:5] offset:0
	global_load_ushort v225, v72, s[0:1] offset:0
	global_load_ushort v226, v72, s[12:13] offset:1024
	global_load_ushort v227, v[74:75], off offset:0
	global_load_ushort v228, v[74:75], off offset:64
	global_load_ushort v229, v72, s[2:3] offset:0
	v_mfma_f32_32x32x2_f32 v[0:15], v240, v244, v[0:15]
	v_mfma_f32_32x32x2_f32 v[32:47], v240, v245, v[32:47]
	ds_read_b128 v[148:151], v76 offset:384
	ds_read_b128 v[152:155], v76 offset:416
	ds_read_b128 v[156:159], v76 offset:448
	ds_read_b128 v[160:163], v76 offset:480
	ds_read_b128 v[164:167], v76 offset:640
	ds_read_b128 v[168:171], v76 offset:672
	ds_read_b128 v[172:175], v76 offset:704
	ds_read_b128 v[176:179], v76 offset:736
	v_mfma_f32_32x32x2_f32 v[16:31], v241, v244, v[16:31]
	v_mfma_f32_32x32x2_f32 v[48:63], v241, v245, v[48:63]
	s_waitcnt vmcnt(18)
	v_lshlrev_b32_e32 v78, 16, v230
	v_mul_f32_e32 v78, 0xbfb8aa3b, v78
	v_exp_f32_e32 v78, v78
	v_lshlrev_b32_e32 v79, 16, v231
	v_lshlrev_b32_e32 v80, 16, v232
	v_mul_f32_e32 v246, v246, v78
	v_mul_f32_e32 v79, v79, v246
	v_mul_f32_e32 v80, v80, v246
	v_rcp_f32_e32 v248, v246
	s_nop 0
	ds_write2st64_b32 v77, v248, v79 offset0:3 offset1:4
	ds_write_b32 v77, v80 offset:1280
	s_waitcnt lgkmcnt(10)
	v_pk_mul_f32 v[64:65], v[0:1], v[192:193]
	v_pk_mul_f32 v[68:69], v[0:1], v[208:209]
	v_pk_fma_f32 v[64:65], v[2:3], v[194:195], v[64:65]
	v_pk_fma_f32 v[68:69], v[2:3], v[210:211], v[68:69]
	v_pk_fma_f32 v[64:65], v[4:5], v[196:197], v[64:65]
	v_pk_fma_f32 v[68:69], v[4:5], v[212:213], v[68:69]
	v_pk_fma_f32 v[64:65], v[6:7], v[198:199], v[64:65]
	v_pk_fma_f32 v[68:69], v[6:7], v[214:215], v[68:69]
	v_pk_fma_f32 v[64:65], v[8:9], v[200:201], v[64:65]
	v_pk_fma_f32 v[68:69], v[8:9], v[216:217], v[68:69]
	v_pk_fma_f32 v[64:65], v[10:11], v[202:203], v[64:65]
	v_pk_fma_f32 v[68:69], v[10:11], v[218:219], v[68:69]
	v_pk_fma_f32 v[64:65], v[12:13], v[204:205], v[64:65]
	v_pk_fma_f32 v[68:69], v[12:13], v[220:221], v[68:69]
	v_pk_fma_f32 v[64:65], v[14:15], v[206:207], v[64:65]
	v_pk_fma_f32 v[68:69], v[14:15], v[222:223], v[68:69]
	v_pk_mul_f32 v[66:67], v[32:33], v[192:193]
	v_pk_mul_f32 v[70:71], v[32:33], v[208:209]
	v_pk_fma_f32 v[66:67], v[34:35], v[194:195], v[66:67]
	v_pk_fma_f32 v[70:71], v[34:35], v[210:211], v[70:71]
	v_pk_fma_f32 v[66:67], v[36:37], v[196:197], v[66:67]
	v_pk_fma_f32 v[70:71], v[36:37], v[212:213], v[70:71]
	v_pk_fma_f32 v[66:67], v[38:39], v[198:199], v[66:67]
	v_pk_fma_f32 v[70:71], v[38:39], v[214:215], v[70:71]
	v_pk_fma_f32 v[66:67], v[40:41], v[200:201], v[66:67]
	v_pk_fma_f32 v[70:71], v[40:41], v[216:217], v[70:71]
	v_pk_fma_f32 v[66:67], v[42:43], v[202:203], v[66:67]
	v_pk_fma_f32 v[70:71], v[42:43], v[218:219], v[70:71]
	v_pk_fma_f32 v[66:67], v[44:45], v[204:205], v[66:67]
	v_pk_fma_f32 v[70:71], v[44:45], v[220:221], v[70:71]
	v_pk_fma_f32 v[66:67], v[46:47], v[206:207], v[66:67]
	v_pk_fma_f32 v[70:71], v[46:47], v[222:223], v[70:71]
	s_waitcnt lgkmcnt(2)
	v_pk_fma_f32 v[64:65], v[16:17], v[148:149], v[64:65]
	v_pk_fma_f32 v[68:69], v[16:17], v[164:165], v[68:69]
	v_pk_fma_f32 v[64:65], v[18:19], v[150:151], v[64:65]
	v_pk_fma_f32 v[68:69], v[18:19], v[166:167], v[68:69]
	v_pk_fma_f32 v[64:65], v[20:21], v[152:153], v[64:65]
	v_pk_fma_f32 v[68:69], v[20:21], v[168:169], v[68:69]
	v_pk_fma_f32 v[64:65], v[22:23], v[154:155], v[64:65]
	v_pk_fma_f32 v[68:69], v[22:23], v[170:171], v[68:69]
	v_pk_fma_f32 v[64:65], v[24:25], v[156:157], v[64:65]
	v_pk_fma_f32 v[68:69], v[24:25], v[172:173], v[68:69]
	v_pk_fma_f32 v[64:65], v[26:27], v[158:159], v[64:65]
	v_pk_fma_f32 v[68:69], v[26:27], v[174:175], v[68:69]
	v_pk_fma_f32 v[64:65], v[28:29], v[160:161], v[64:65]
	v_pk_fma_f32 v[68:69], v[28:29], v[176:177], v[68:69]
	v_pk_fma_f32 v[64:65], v[30:31], v[162:163], v[64:65]
	v_pk_fma_f32 v[68:69], v[30:31], v[178:179], v[68:69]
	v_pk_fma_f32 v[66:67], v[48:49], v[148:149], v[66:67]
	v_pk_fma_f32 v[70:71], v[48:49], v[164:165], v[70:71]
	v_pk_fma_f32 v[66:67], v[50:51], v[150:151], v[66:67]
	v_pk_fma_f32 v[70:71], v[50:51], v[166:167], v[70:71]
	v_pk_fma_f32 v[66:67], v[52:53], v[152:153], v[66:67]
	v_pk_fma_f32 v[70:71], v[52:53], v[168:169], v[70:71]
	v_pk_fma_f32 v[66:67], v[54:55], v[154:155], v[66:67]
	v_pk_fma_f32 v[70:71], v[54:55], v[170:171], v[70:71]
	v_pk_fma_f32 v[66:67], v[56:57], v[156:157], v[66:67]
	v_pk_fma_f32 v[70:71], v[56:57], v[172:173], v[70:71]
	v_pk_fma_f32 v[66:67], v[58:59], v[158:159], v[66:67]
	v_pk_fma_f32 v[70:71], v[58:59], v[174:175], v[70:71]
	v_pk_fma_f32 v[66:67], v[60:61], v[160:161], v[66:67]
	v_pk_fma_f32 v[70:71], v[60:61], v[176:177], v[70:71]
	v_pk_fma_f32 v[66:67], v[62:63], v[162:163], v[66:67]
	v_pk_fma_f32 v[70:71], v[62:63], v[178:179], v[70:71]
	ds_read_b32 v249, v251 offset:768
	ds_read_b32 v250, v251 offset:896
	v_lshlrev_b32_e32 v240, 16, v233
	v_lshlrev_b32_e32 v241, 16, v234
	s_waitcnt lgkmcnt(0)
; template <bool ID> __device__ __forceinline__ void rwkv_scan(const bf16_t* __restrict__ R, const bf16_t* __restrict__ EW, const bf16_t* __restrict__ K, const bf16_t* __restrict__ V, ...
;     ...
;     for (int s = 0; s < nsteps; ++s) {
;         L[lane] = bf2f(q2[4]); L[64 + lane] = __expf(-bf2f(q1[1])); L[128 + lane] = bf2f(q1[5]); L[192 + lane] = bf2f(q1[2]); L[256 + lane] = bf2f(q1[0]);
;         const float v = bf2f(q1[3]);
; #pragma unroll
;         for (int j = 0; j < 6; ++j) q1[j] = q2[j];
;         { const unsigned o = base + (unsigned)(s + 2 < nsteps ? s + 2 : nsteps - 1) * 512u; q2[0] = R[o]; q2[1] = EW[o]; q2[2] = K[o]; q2[3] = V[o]; q2[4] = A[o]; q2[5] = B[o]; }
;         const f2 sav2 = {sav, sav}, sai2 = {sai, sai}, v2 = {v, v};
;         f2 yv = {0.f, 0.f}, yi = {0.f, 0.f}, yv1 = {0.f, 0.f}, yi1 = {0.f, 0.f}, nv = {0.f, 0.f}, ni = {0.f, 0.f}, nv1 = {0.f, 0.f}, ni1 = {0.f, 0.f};
;         f32x4 ca = pa[0], cw = pa[16], cb = pa[32], ck = pa[48], cr = pa[64];
; #pragma unroll
;         for (int q = 0; q < 16; ++q) {
;             const f32x4 a4 = ca, w4 = cw, b4 = cb, k4 = ck, r4 = cr;
;             if (q < 15) { ca = pa[1 + q]; cw = pa[17 + q]; cb = pa[33 + q]; ck = pa[49 + q]; cr = pa[65 + q]; }
;             __builtin_amdgcn_sched_barrier(0);
;             { const f2 a2 = {a4[0], a4[1]}, w2 = {w4[0], w4[1]}, b2 = {b4[0], b4[1]}, k2 = {k4[0], k4[1]}, r2 = {r4[0], r4[1]};
;               f2 tv = sav2 * b2; tv = pfma(v2, k2, tv); Sv[2 * q] = pfma(Sv[2 * q], w2, tv); yv = pfma(Sv[2 * q], r2, yv); nv = pfma(Sv[2 * q], a2, nv);
;               if (ID) { const f2 ti = sai2 * b2; Si[2 * q] = pfma(Si[2 * q], w2, ti); yi = pfma(Si[2 * q], r2, yi); ni = pfma(Si[2 * q], a2, ni); } }
;             { const f2 a2 = {a4[2], a4[3]}, w2 = {w4[2], w4[3]}, b2 = {b4[2], b4[3]}, k2 = {k4[2], k4[3]}, r2 = {r4[2], r4[3]};
;               f2 tv = sav2 * b2; tv = pfma(v2, k2, tv); Sv[2 * q + 1] = pfma(Sv[2 * q + 1], w2, tv); yv1 = pfma(Sv[2 * q + 1], r2, yv1); nv1 = pfma(Sv[2 * q + 1], a2, nv1);
;               if (ID) { const f2 ti = sai2 * b2; Si[2 * q + 1] = pfma(Si[2 * q + 1], w2, ti); yi1 = pfma(Si[2 * q + 1], r2, yi1); ni1 = pfma(Si[2 * q + 1], a2, ni1); } }
;         }
;         sav = (nv[0] + nv[1]) + (nv1[0] + nv1[1]); sai = (ni[0] + ni[1]) + (ni1[0] + ni1[1]);
;         const unsigned cbo = base + (unsigned)s * 512u;
	v_mul_f32_e32 v240, v240, v249
	v_mul_f32_e32 v241, v241, v250
	v_add_f32_e32 v68, v68, v69
	v_add_f32_e32 v70, v70, v71
	v_add_f32_e32 v64, v64, v65
	v_add_f32_e32 v66, v66, v67
	v_lshlrev_b32_e32 v245, 16, v235
	v_permlane32_swap_b32_e32 v68, v70
	v_permlane32_swap_b32_e32 v64, v66
	v_add_f32_e32 v244, v68, v70
	v_add_f32_e32 v64, v64, v66
	v_bfe_u32 v66, v64, 16, 1
	v_add3_u32 v66, v64, v66, s69
	v_permlane32_swap_b32_e32 v244, v245
	global_store_short_d16_hi v72, v66, s[22:23] offset:-4096
	v_add_u32_e32 v72, 0x400, v72
	v_lshl_add_u64 v[74:75], v[74:75], 0, s[54:55]
	ds_read_b128 v[148:151], v76 offset:1024
	ds_read_b128 v[152:155], v76 offset:1056
	ds_read_b128 v[156:159], v76 offset:1088
	ds_read_b128 v[160:163], v76 offset:1120
	ds_read_b128 v[164:167], v76 offset:1280
	ds_read_b128 v[168:171], v76 offset:1312
	ds_read_b128 v[172:175], v76 offset:1344
	ds_read_b128 v[176:179], v76 offset:1376
	global_load_ushort v230, v72, s[4:5] offset:0
	global_load_ushort v231, v72, s[0:1] offset:0
	global_load_ushort v232, v72, s[12:13] offset:1024
	global_load_ushort v233, v[74:75], off offset:0
	global_load_ushort v234, v[74:75], off offset:64
	global_load_ushort v235, v72, s[2:3] offset:0
	v_mfma_f32_32x32x2_f32 v[0:15], v240, v244, v[0:15]
	v_mfma_f32_32x32x2_f32 v[32:47], v240, v245, v[32:47]
	ds_read_b128 v[192:195], v76 offset:1152
	ds_read_b128 v[196:199], v76 offset:1184
	ds_read_b128 v[200:203], v76 offset:1216
	ds_read_b128 v[204:207], v76 offset:1248
	ds_read_b128 v[208:211], v76 offset:1408
	ds_read_b128 v[212:215], v76 offset:1440
	ds_read_b128 v[216:219], v76 offset:1472
	ds_read_b128 v[220:223], v76 offset:1504
	v_mfma_f32_32x32x2_f32 v[16:31], v241, v244, v[16:31]
	v_mfma_f32_32x32x2_f32 v[48:63], v241, v245, v[48:63]
	s_waitcnt vmcnt(19)
	v_lshlrev_b32_e32 v78, 16, v82
	v_mul_f32_e32 v78, 0xbfb8aa3b, v78
	v_exp_f32_e32 v78, v78
	v_lshlrev_b32_e32 v79, 16, v83
	v_lshlrev_b32_e32 v80, 16, v84
	v_mul_f32_e32 v246, v246, v78
	v_mul_f32_e32 v79, v79, v246
	v_mul_f32_e32 v80, v80, v246
	v_rcp_f32_e32 v248, v246
	s_nop 0
	ds_write2st64_b32 v77, v248, v79 offset0:0 offset1:1
	ds_write_b32 v77, v80 offset:512
	s_waitcnt lgkmcnt(10)
	v_pk_mul_f32 v[64:65], v[0:1], v[148:149]
	v_pk_mul_f32 v[68:69], v[0:1], v[164:165]
	v_pk_fma_f32 v[64:65], v[2:3], v[150:151], v[64:65]
	v_pk_fma_f32 v[68:69], v[2:3], v[166:167], v[68:69]
	v_pk_fma_f32 v[64:65], v[4:5], v[152:153], v[64:65]
	v_pk_fma_f32 v[68:69], v[4:5], v[168:169], v[68:69]
	v_pk_fma_f32 v[64:65], v[6:7], v[154:155], v[64:65]
	v_pk_fma_f32 v[68:69], v[6:7], v[170:171], v[68:69]
	v_pk_fma_f32 v[64:65], v[8:9], v[156:157], v[64:65]
	v_pk_fma_f32 v[68:69], v[8:9], v[172:173], v[68:69]
	v_pk_fma_f32 v[64:65], v[10:11], v[158:159], v[64:65]
	v_pk_fma_f32 v[68:69], v[10:11], v[174:175], v[68:69]
	v_pk_fma_f32 v[64:65], v[12:13], v[160:161], v[64:65]
	v_pk_fma_f32 v[68:69], v[12:13], v[176:177], v[68:69]
	v_pk_fma_f32 v[64:65], v[14:15], v[162:163], v[64:65]
	v_pk_fma_f32 v[68:69], v[14:15], v[178:179], v[68:69]
	v_pk_mul_f32 v[66:67], v[32:33], v[148:149]
	v_pk_mul_f32 v[70:71], v[32:33], v[164:165]
	v_pk_fma_f32 v[66:67], v[34:35], v[150:151], v[66:67]
	v_pk_fma_f32 v[70:71], v[34:35], v[166:167], v[70:71]
	v_pk_fma_f32 v[66:67], v[36:37], v[152:153], v[66:67]
	v_pk_fma_f32 v[70:71], v[36:37], v[168:169], v[70:71]
	v_pk_fma_f32 v[66:67], v[38:39], v[154:155], v[66:67]
	v_pk_fma_f32 v[70:71], v[38:39], v[170:171], v[70:71]
	v_pk_fma_f32 v[66:67], v[40:41], v[156:157], v[66:67]
	v_pk_fma_f32 v[70:71], v[40:41], v[172:173], v[70:71]
	v_pk_fma_f32 v[66:67], v[42:43], v[158:159], v[66:67]
	v_pk_fma_f32 v[70:71], v[42:43], v[174:175], v[70:71]
	v_pk_fma_f32 v[66:67], v[44:45], v[160:161], v[66:67]
	v_pk_fma_f32 v[70:71], v[44:45], v[176:177], v[70:71]
	v_pk_fma_f32 v[66:67], v[46:47], v[162:163], v[66:67]
	v_pk_fma_f32 v[70:71], v[46:47], v[178:179], v[70:71]
	s_waitcnt lgkmcnt(2)
	v_pk_fma_f32 v[64:65], v[16:17], v[192:193], v[64:65]
	v_pk_fma_f32 v[68:69], v[16:17], v[208:209], v[68:69]
	v_pk_fma_f32 v[64:65], v[18:19], v[194:195], v[64:65]
	v_pk_fma_f32 v[68:69], v[18:19], v[210:211], v[68:69]
	v_pk_fma_f32 v[64:65], v[20:21], v[196:197], v[64:65]
	v_pk_fma_f32 v[68:69], v[20:21], v[212:213], v[68:69]
	v_pk_fma_f32 v[64:65], v[22:23], v[198:199], v[64:65]
	v_pk_fma_f32 v[68:69], v[22:23], v[214:215], v[68:69]
	v_pk_fma_f32 v[64:65], v[24:25], v[200:201], v[64:65]
	v_pk_fma_f32 v[68:69], v[24:25], v[216:217], v[68:69]
	v_pk_fma_f32 v[64:65], v[26:27], v[202:203], v[64:65]
	v_pk_fma_f32 v[68:69], v[26:27], v[218:219], v[68:69]
	v_pk_fma_f32 v[64:65], v[28:29], v[204:205], v[64:65]
	v_pk_fma_f32 v[68:69], v[28:29], v[220:221], v[68:69]
	v_pk_fma_f32 v[64:65], v[30:31], v[206:207], v[64:65]
	v_pk_fma_f32 v[68:69], v[30:31], v[222:223], v[68:69]
	v_pk_fma_f32 v[66:67], v[48:49], v[192:193], v[66:67]
	v_pk_fma_f32 v[70:71], v[48:49], v[208:209], v[70:71]
	v_pk_fma_f32 v[66:67], v[50:51], v[194:195], v[66:67]
	v_pk_fma_f32 v[70:71], v[50:51], v[210:211], v[70:71]
	v_pk_fma_f32 v[66:67], v[52:53], v[196:197], v[66:67]
	v_pk_fma_f32 v[70:71], v[52:53], v[212:213], v[70:71]
	v_pk_fma_f32 v[66:67], v[54:55], v[198:199], v[66:67]
	v_pk_fma_f32 v[70:71], v[54:55], v[214:215], v[70:71]
	v_pk_fma_f32 v[66:67], v[56:57], v[200:201], v[66:67]
	v_pk_fma_f32 v[70:71], v[56:57], v[216:217], v[70:71]
	v_pk_fma_f32 v[66:67], v[58:59], v[202:203], v[66:67]
	v_pk_fma_f32 v[70:71], v[58:59], v[218:219], v[70:71]
	v_pk_fma_f32 v[66:67], v[60:61], v[204:205], v[66:67]
	v_pk_fma_f32 v[70:71], v[60:61], v[220:221], v[70:71]
	v_pk_fma_f32 v[66:67], v[62:63], v[206:207], v[66:67]
	v_pk_fma_f32 v[70:71], v[62:63], v[222:223], v[70:71]
	ds_read_b32 v249, v251 offset:0
	ds_read_b32 v250, v251 offset:128
	v_lshlrev_b32_e32 v240, 16, v85
	v_lshlrev_b32_e32 v241, 16, v86
	s_waitcnt lgkmcnt(0)
; template <bool ID> __device__ __forceinline__ void rwkv_scan(const bf16_t* __restrict__ R, const bf16_t* __restrict__ EW, const bf16_t* __restrict__ K, const bf16_t* __restrict__ V, ...
;     ...
;     for (int s = 0; s < nsteps; ++s) {
;         L[lane] = bf2f(q2[4]); L[64 + lane] = __expf(-bf2f(q1[1])); L[128 + lane] = bf2f(q1[5]); L[192 + lane] = bf2f(q1[2]); L[256 + lane] = bf2f(q1[0]);
;         const float v = bf2f(q1[3]);
; #pragma unroll
;         for (int j = 0; j < 6; ++j) q1[j] = q2[j];
;         { const unsigned o = base + (unsigned)(s + 2 < nsteps ? s + 2 : nsteps - 1) * 512u; q2[0] = R[o]; q2[1] = EW[o]; q2[2] = K[o]; q2[3] = V[o]; q2[4] = A[o]; q2[5] = B[o]; }
;         const f2 sav2 = {sav, sav}, sai2 = {sai, sai}, v2 = {v, v};
;         f2 yv = {0.f, 0.f}, yi = {0.f, 0.f}, yv1 = {0.f, 0.f}, yi1 = {0.f, 0.f}, nv = {0.f, 0.f}, ni = {0.f, 0.f}, nv1 = {0.f, 0.f}, ni1 = {0.f, 0.f};
;         f32x4 ca = pa[0], cw = pa[16], cb = pa[32], ck = pa[48], cr = pa[64];
; #pragma unroll
;         for (int q = 0; q < 16; ++q) {
;             const f32x4 a4 = ca, w4 = cw, b4 = cb, k4 = ck, r4 = cr;
;             if (q < 15) { ca = pa[1 + q]; cw = pa[17 + q]; cb = pa[33 + q]; ck = pa[49 + q]; cr = pa[65 + q]; }
;             __builtin_amdgcn_sched_barrier(0);
;             { const f2 a2 = {a4[0], a4[1]}, w2 = {w4[0], w4[1]}, b2 = {b4[0], b4[1]}, k2 = {k4[0], k4[1]}, r2 = {r4[0], r4[1]};
;               f2 tv = sav2 * b2; tv = pfma(v2, k2, tv); Sv[2 * q] = pfma(Sv[2 * q], w2, tv); yv = pfma(Sv[2 * q], r2, yv); nv = pfma(Sv[2 * q], a2, nv);
;               if (ID) { const f2 ti = sai2 * b2; Si[2 * q] = pfma(Si[2 * q], w2, ti); yi = pfma(Si[2 * q], r2, yi); ni = pfma(Si[2 * q], a2, ni); } }
;             { const f2 a2 = {a4[2], a4[3]}, w2 = {w4[2], w4[3]}, b2 = {b4[2], b4[3]}, k2 = {k4[2], k4[3]}, r2 = {r4[2], r4[3]};
;               f2 tv = sav2 * b2; tv = pfma(v2, k2, tv); Sv[2 * q + 1] = pfma(Sv[2 * q + 1], w2, tv); yv1 = pfma(Sv[2 * q + 1], r2, yv1); nv1 = pfma(Sv[2 * q + 1], a2, nv1);
;               if (ID) { const f2 ti = sai2 * b2; Si[2 * q + 1] = pfma(Si[2 * q + 1], w2, ti); yi1 = pfma(Si[2 * q + 1], r2, yi1); ni1 = pfma(Si[2 * q + 1], a2, ni1); } }
;         }
;         sav = (nv[0] + nv[1]) + (nv1[0] + nv1[1]); sai = (ni[0] + ni[1]) + (ni1[0] + ni1[1]);
;         const unsigned cbo = base + (unsigned)s * 512u;
	v_mul_f32_e32 v240, v240, v249
	v_mul_f32_e32 v241, v241, v250
	v_add_f32_e32 v68, v68, v69
	v_add_f32_e32 v70, v70, v71
	v_add_f32_e32 v64, v64, v65
	v_add_f32_e32 v66, v66, v67
	v_lshlrev_b32_e32 v245, 16, v87
	v_permlane32_swap_b32_e32 v68, v70
	v_permlane32_swap_b32_e32 v64, v66
	v_add_f32_e32 v244, v68, v70
	v_add_f32_e32 v64, v64, v66
	v_bfe_u32 v66, v64, 16, 1
	v_add3_u32 v66, v64, v66, s69
	v_permlane32_swap_b32_e32 v244, v245
	global_store_short_d16_hi v72, v66, s[22:23] offset:-4096
	v_add_u32_e32 v72, 0x400, v72
	v_lshl_add_u64 v[74:75], v[74:75], 0, s[54:55]
	ds_read_b128 v[192:195], v76 offset:256
	ds_read_b128 v[196:199], v76 offset:288
	ds_read_b128 v[200:203], v76 offset:320
	ds_read_b128 v[204:207], v76 offset:352
	ds_read_b128 v[208:211], v76 offset:512
	ds_read_b128 v[212:215], v76 offset:544
	ds_read_b128 v[216:219], v76 offset:576
	ds_read_b128 v[220:223], v76 offset:608
	global_load_ushort v82, v72, s[4:5] offset:0
	global_load_ushort v83, v72, s[0:1] offset:0
	global_load_ushort v84, v72, s[12:13] offset:1024
	global_load_ushort v85, v[74:75], off offset:0
	global_load_ushort v86, v[74:75], off offset:64
	global_load_ushort v87, v72, s[2:3] offset:0
	v_mfma_f32_32x32x2_f32 v[0:15], v240, v244, v[0:15]
	v_mfma_f32_32x32x2_f32 v[32:47], v240, v245, v[32:47]
	ds_read_b128 v[148:151], v76 offset:384
	ds_read_b128 v[152:155], v76 offset:416
	ds_read_b128 v[156:159], v76 offset:448
	ds_read_b128 v[160:163], v76 offset:480
	ds_read_b128 v[164:167], v76 offset:640
	ds_read_b128 v[168:171], v76 offset:672
	ds_read_b128 v[172:175], v76 offset:704
	ds_read_b128 v[176:179], v76 offset:736
	v_mfma_f32_32x32x2_f32 v[16:31], v241, v244, v[16:31]
	v_mfma_f32_32x32x2_f32 v[48:63], v241, v245, v[48:63]
	s_waitcnt vmcnt(20)
	v_lshlrev_b32_e32 v78, 16, v88
	v_mul_f32_e32 v78, 0xbfb8aa3b, v78
	v_exp_f32_e32 v78, v78
	v_lshlrev_b32_e32 v79, 16, v89
	v_lshlrev_b32_e32 v80, 16, v90
	v_mul_f32_e32 v246, v246, v78
	v_mul_f32_e32 v79, v79, v246
	v_mul_f32_e32 v80, v80, v246
	v_rcp_f32_e32 v248, v246
	s_nop 0
	ds_write2st64_b32 v77, v248, v79 offset0:3 offset1:4
	ds_write_b32 v77, v80 offset:1280
	s_waitcnt lgkmcnt(10)
	v_pk_mul_f32 v[64:65], v[0:1], v[192:193]
	v_pk_mul_f32 v[68:69], v[0:1], v[208:209]
	v_pk_fma_f32 v[64:65], v[2:3], v[194:195], v[64:65]
	v_pk_fma_f32 v[68:69], v[2:3], v[210:211], v[68:69]
	v_pk_fma_f32 v[64:65], v[4:5], v[196:197], v[64:65]
	v_pk_fma_f32 v[68:69], v[4:5], v[212:213], v[68:69]
	v_pk_fma_f32 v[64:65], v[6:7], v[198:199], v[64:65]
	v_pk_fma_f32 v[68:69], v[6:7], v[214:215], v[68:69]
	v_pk_fma_f32 v[64:65], v[8:9], v[200:201], v[64:65]
	v_pk_fma_f32 v[68:69], v[8:9], v[216:217], v[68:69]
	v_pk_fma_f32 v[64:65], v[10:11], v[202:203], v[64:65]
	v_pk_fma_f32 v[68:69], v[10:11], v[218:219], v[68:69]
	v_pk_fma_f32 v[64:65], v[12:13], v[204:205], v[64:65]
	v_pk_fma_f32 v[68:69], v[12:13], v[220:221], v[68:69]
	v_pk_fma_f32 v[64:65], v[14:15], v[206:207], v[64:65]
	v_pk_fma_f32 v[68:69], v[14:15], v[222:223], v[68:69]
	v_pk_mul_f32 v[66:67], v[32:33], v[192:193]
	v_pk_mul_f32 v[70:71], v[32:33], v[208:209]
	v_pk_fma_f32 v[66:67], v[34:35], v[194:195], v[66:67]
	v_pk_fma_f32 v[70:71], v[34:35], v[210:211], v[70:71]
	v_pk_fma_f32 v[66:67], v[36:37], v[196:197], v[66:67]
	v_pk_fma_f32 v[70:71], v[36:37], v[212:213], v[70:71]
	v_pk_fma_f32 v[66:67], v[38:39], v[198:199], v[66:67]
	v_pk_fma_f32 v[70:71], v[38:39], v[214:215], v[70:71]
	v_pk_fma_f32 v[66:67], v[40:41], v[200:201], v[66:67]
	v_pk_fma_f32 v[70:71], v[40:41], v[216:217], v[70:71]
	v_pk_fma_f32 v[66:67], v[42:43], v[202:203], v[66:67]
	v_pk_fma_f32 v[70:71], v[42:43], v[218:219], v[70:71]
	v_pk_fma_f32 v[66:67], v[44:45], v[204:205], v[66:67]
	v_pk_fma_f32 v[70:71], v[44:45], v[220:221], v[70:71]
	v_pk_fma_f32 v[66:67], v[46:47], v[206:207], v[66:67]
	v_pk_fma_f32 v[70:71], v[46:47], v[222:223], v[70:71]
	s_waitcnt lgkmcnt(2)
	v_pk_fma_f32 v[64:65], v[16:17], v[148:149], v[64:65]
	v_pk_fma_f32 v[68:69], v[16:17], v[164:165], v[68:69]
	v_pk_fma_f32 v[64:65], v[18:19], v[150:151], v[64:65]
	v_pk_fma_f32 v[68:69], v[18:19], v[166:167], v[68:69]
	v_pk_fma_f32 v[64:65], v[20:21], v[152:153], v[64:65]
	v_pk_fma_f32 v[68:69], v[20:21], v[168:169], v[68:69]
	v_pk_fma_f32 v[64:65], v[22:23], v[154:155], v[64:65]
	v_pk_fma_f32 v[68:69], v[22:23], v[170:171], v[68:69]
	v_pk_fma_f32 v[64:65], v[24:25], v[156:157], v[64:65]
	v_pk_fma_f32 v[68:69], v[24:25], v[172:173], v[68:69]
	v_pk_fma_f32 v[64:65], v[26:27], v[158:159], v[64:65]
	v_pk_fma_f32 v[68:69], v[26:27], v[174:175], v[68:69]
	v_pk_fma_f32 v[64:65], v[28:29], v[160:161], v[64:65]
	v_pk_fma_f32 v[68:69], v[28:29], v[176:177], v[68:69]
	v_pk_fma_f32 v[64:65], v[30:31], v[162:163], v[64:65]
	v_pk_fma_f32 v[68:69], v[30:31], v[178:179], v[68:69]
	v_pk_fma_f32 v[66:67], v[48:49], v[148:149], v[66:67]
	v_pk_fma_f32 v[70:71], v[48:49], v[164:165], v[70:71]
	v_pk_fma_f32 v[66:67], v[50:51], v[150:151], v[66:67]
	v_pk_fma_f32 v[70:71], v[50:51], v[166:167], v[70:71]
	v_pk_fma_f32 v[66:67], v[52:53], v[152:153], v[66:67]
	v_pk_fma_f32 v[70:71], v[52:53], v[168:169], v[70:71]
	v_pk_fma_f32 v[66:67], v[54:55], v[154:155], v[66:67]
	v_pk_fma_f32 v[70:71], v[54:55], v[170:171], v[70:71]
	v_pk_fma_f32 v[66:67], v[56:57], v[156:157], v[66:67]
	v_pk_fma_f32 v[70:71], v[56:57], v[172:173], v[70:71]
	v_pk_fma_f32 v[66:67], v[58:59], v[158:159], v[66:67]
	v_pk_fma_f32 v[70:71], v[58:59], v[174:175], v[70:71]
	v_pk_fma_f32 v[66:67], v[60:61], v[160:161], v[66:67]
	v_pk_fma_f32 v[70:71], v[60:61], v[176:177], v[70:71]
	v_pk_fma_f32 v[66:67], v[62:63], v[162:163], v[66:67]
	v_pk_fma_f32 v[70:71], v[62:63], v[178:179], v[70:71]
	ds_read_b32 v249, v251 offset:768
	ds_read_b32 v250, v251 offset:896
	v_lshlrev_b32_e32 v240, 16, v91
	v_lshlrev_b32_e32 v241, 16, v92
	s_waitcnt lgkmcnt(0)
	v_mul_f32_e32 v240, v240, v249
	v_mul_f32_e32 v241, v241, v250
	v_add_f32_e32 v68, v68, v69
	v_add_f32_e32 v70, v70, v71
	v_add_f32_e32 v64, v64, v65
	v_add_f32_e32 v66, v66, v67
	v_lshlrev_b32_e32 v245, 16, v93
	v_permlane32_swap_b32_e32 v68, v70
	v_permlane32_swap_b32_e32 v64, v66
	v_add_f32_e32 v244, v68, v70
	v_add_f32_e32 v64, v64, v66
	v_bfe_u32 v66, v64, 16, 1
	v_add3_u32 v66, v64, v66, s69
	v_permlane32_swap_b32_e32 v244, v245
	global_store_short_d16_hi v72, v66, s[22:23] offset:-4096
	v_add_u32_e32 v72, 0x400, v72
	v_lshl_add_u64 v[74:75], v[74:75], 0, s[54:55]
	s_and_b32 s14, s41, 15
	s_cmp_eq_u32 s14, 15
	s_cbranch_scc1 .Lscan_v_s3x
; template <bool ID> __device__ __forceinline__ void rwkv_scan(const bf16_t* __restrict__ R, const bf16_t* __restrict__ EW, const bf16_t* __restrict__ K, const bf16_t* __restrict__ V, ...
;     ...
;     for (int s = 0; s < nsteps; ++s) {
;         L[lane] = bf2f(q2[4]); L[64 + lane] = __expf(-bf2f(q1[1])); L[128 + lane] = bf2f(q1[5]); L[192 + lane] = bf2f(q1[2]); L[256 + lane] = bf2f(q1[0]);
;         const float v = bf2f(q1[3]);
; #pragma unroll
;         for (int j = 0; j < 6; ++j) q1[j] = q2[j];
;         { const unsigned o = base + (unsigned)(s + 2 < nsteps ? s + 2 : nsteps - 1) * 512u; q2[0] = R[o]; q2[1] = EW[o]; q2[2] = K[o]; q2[3] = V[o]; q2[4] = A[o]; q2[5] = B[o]; }
;         const f2 sav2 = {sav, sav}, sai2 = {sai, sai}, v2 = {v, v};
;         f2 yv = {0.f, 0.f}, yi = {0.f, 0.f}, yv1 = {0.f, 0.f}, yi1 = {0.f, 0.f}, nv = {0.f, 0.f}, ni = {0.f, 0.f}, nv1 = {0.f, 0.f}, ni1 = {0.f, 0.f};
;         f32x4 ca = pa[0], cw = pa[16], cb = pa[32], ck = pa[48], cr = pa[64];
; #pragma unroll
;         for (int q = 0; q < 16; ++q) {
;             const f32x4 a4 = ca, w4 = cw, b4 = cb, k4 = ck, r4 = cr;
;             if (q < 15) { ca = pa[1 + q]; cw = pa[17 + q]; cb = pa[33 + q]; ck = pa[49 + q]; cr = pa[65 + q]; }
;             __builtin_amdgcn_sched_barrier(0);
;             { const f2 a2 = {a4[0], a4[1]}, w2 = {w4[0], w4[1]}, b2 = {b4[0], b4[1]}, k2 = {k4[0], k4[1]}, r2 = {r4[0], r4[1]};
;               f2 tv = sav2 * b2; tv = pfma(v2, k2, tv); Sv[2 * q] = pfma(Sv[2 * q], w2, tv); yv = pfma(Sv[2 * q], r2, yv); nv = pfma(Sv[2 * q], a2, nv);
;               if (ID) { const f2 ti = sai2 * b2; Si[2 * q] = pfma(Si[2 * q], w2, ti); yi = pfma(Si[2 * q], r2, yi); ni = pfma(Si[2 * q], a2, ni); } }
;             { const f2 a2 = {a4[2], a4[3]}, w2 = {w4[2], w4[3]}, b2 = {b4[2], b4[3]}, k2 = {k4[2], k4[3]}, r2 = {r4[2], r4[3]};
;               f2 tv = sav2 * b2; tv = pfma(v2, k2, tv); Sv[2 * q + 1] = pfma(Sv[2 * q + 1], w2, tv); yv1 = pfma(Sv[2 * q + 1], r2, yv1); nv1 = pfma(Sv[2 * q + 1], a2, nv1);
;               if (ID) { const f2 ti = sai2 * b2; Si[2 * q + 1] = pfma(Si[2 * q + 1], w2, ti); yi1 = pfma(Si[2 * q + 1], r2, yi1); ni1 = pfma(Si[2 * q + 1], a2, ni1); } }
;         }
;         sav = (nv[0] + nv[1]) + (nv1[0] + nv1[1]); sai = (ni[0] + ni[1]) + (ni1[0] + ni1[1]);
;         const unsigned cbo = base + (unsigned)s * 512u;
	ds_read_b128 v[148:151], v76 offset:1024
	ds_read_b128 v[152:155], v76 offset:1056
	ds_read_b128 v[156:159], v76 offset:1088
	ds_read_b128 v[160:163], v76 offset:1120
	ds_read_b128 v[164:167], v76 offset:1280
	ds_read_b128 v[168:171], v76 offset:1312
	ds_read_b128 v[172:175], v76 offset:1344
	ds_read_b128 v[176:179], v76 offset:1376
	global_load_ushort v88, v72, s[4:5] offset:0
	global_load_ushort v89, v72, s[0:1] offset:0
	global_load_ushort v90, v72, s[12:13] offset:1024
	global_load_ushort v91, v[74:75], off offset:0
	global_load_ushort v92, v[74:75], off offset:64
	global_load_ushort v93, v72, s[2:3] offset:0
	v_mfma_f32_32x32x2_f32 v[0:15], v240, v244, v[0:15]
	v_mfma_f32_32x32x2_f32 v[32:47], v240, v245, v[32:47]
	ds_read_b128 v[192:195], v76 offset:1152
	ds_read_b128 v[196:199], v76 offset:1184
	ds_read_b128 v[200:203], v76 offset:1216
	ds_read_b128 v[204:207], v76 offset:1248
	ds_read_b128 v[208:211], v76 offset:1408
	ds_read_b128 v[212:215], v76 offset:1440
	ds_read_b128 v[216:219], v76 offset:1472
	ds_read_b128 v[220:223], v76 offset:1504
	v_mfma_f32_32x32x2_f32 v[16:31], v241, v244, v[16:31]
	v_mfma_f32_32x32x2_f32 v[48:63], v241, v245, v[48:63]
	s_waitcnt vmcnt(21)
	v_lshlrev_b32_e32 v78, 16, v224
	v_mul_f32_e32 v78, 0xbfb8aa3b, v78
	v_exp_f32_e32 v78, v78
	v_lshlrev_b32_e32 v79, 16, v225
	v_lshlrev_b32_e32 v80, 16, v226
	v_mul_f32_e32 v246, v246, v78
	v_mul_f32_e32 v79, v79, v246
	v_mul_f32_e32 v80, v80, v246
	v_rcp_f32_e32 v248, v246
	s_nop 0
	ds_write2st64_b32 v77, v248, v79 offset0:0 offset1:1
	ds_write_b32 v77, v80 offset:512
	s_waitcnt lgkmcnt(10)
	v_pk_mul_f32 v[64:65], v[0:1], v[148:149]
	v_pk_mul_f32 v[68:69], v[0:1], v[164:165]
	v_pk_fma_f32 v[64:65], v[2:3], v[150:151], v[64:65]
	v_pk_fma_f32 v[68:69], v[2:3], v[166:167], v[68:69]
	v_pk_fma_f32 v[64:65], v[4:5], v[152:153], v[64:65]
	v_pk_fma_f32 v[68:69], v[4:5], v[168:169], v[68:69]
	v_pk_fma_f32 v[64:65], v[6:7], v[154:155], v[64:65]
	v_pk_fma_f32 v[68:69], v[6:7], v[170:171], v[68:69]
	v_pk_fma_f32 v[64:65], v[8:9], v[156:157], v[64:65]
	v_pk_fma_f32 v[68:69], v[8:9], v[172:173], v[68:69]
	v_pk_fma_f32 v[64:65], v[10:11], v[158:159], v[64:65]
	v_pk_fma_f32 v[68:69], v[10:11], v[174:175], v[68:69]
	v_pk_fma_f32 v[64:65], v[12:13], v[160:161], v[64:65]
	v_pk_fma_f32 v[68:69], v[12:13], v[176:177], v[68:69]
	v_pk_fma_f32 v[64:65], v[14:15], v[162:163], v[64:65]
	v_pk_fma_f32 v[68:69], v[14:15], v[178:179], v[68:69]
	v_pk_mul_f32 v[66:67], v[32:33], v[148:149]
	v_pk_mul_f32 v[70:71], v[32:33], v[164:165]
	v_pk_fma_f32 v[66:67], v[34:35], v[150:151], v[66:67]
	v_pk_fma_f32 v[70:71], v[34:35], v[166:167], v[70:71]
	v_pk_fma_f32 v[66:67], v[36:37], v[152:153], v[66:67]
	v_pk_fma_f32 v[70:71], v[36:37], v[168:169], v[70:71]
	v_pk_fma_f32 v[66:67], v[38:39], v[154:155], v[66:67]
	v_pk_fma_f32 v[70:71], v[38:39], v[170:171], v[70:71]
	v_pk_fma_f32 v[66:67], v[40:41], v[156:157], v[66:67]
	v_pk_fma_f32 v[70:71], v[40:41], v[172:173], v[70:71]
	v_pk_fma_f32 v[66:67], v[42:43], v[158:159], v[66:67]
	v_pk_fma_f32 v[70:71], v[42:43], v[174:175], v[70:71]
	v_pk_fma_f32 v[66:67], v[44:45], v[160:161], v[66:67]
	v_pk_fma_f32 v[70:71], v[44:45], v[176:177], v[70:71]
	v_pk_fma_f32 v[66:67], v[46:47], v[162:163], v[66:67]
	v_pk_fma_f32 v[70:71], v[46:47], v[178:179], v[70:71]
	s_waitcnt lgkmcnt(2)
	v_pk_fma_f32 v[64:65], v[16:17], v[192:193], v[64:65]
	v_pk_fma_f32 v[68:69], v[16:17], v[208:209], v[68:69]
	v_pk_fma_f32 v[64:65], v[18:19], v[194:195], v[64:65]
	v_pk_fma_f32 v[68:69], v[18:19], v[210:211], v[68:69]
	v_pk_fma_f32 v[64:65], v[20:21], v[196:197], v[64:65]
	v_pk_fma_f32 v[68:69], v[20:21], v[212:213], v[68:69]
	v_pk_fma_f32 v[64:65], v[22:23], v[198:199], v[64:65]
	v_pk_fma_f32 v[68:69], v[22:23], v[214:215], v[68:69]
	v_pk_fma_f32 v[64:65], v[24:25], v[200:201], v[64:65]
	v_pk_fma_f32 v[68:69], v[24:25], v[216:217], v[68:69]
	v_pk_fma_f32 v[64:65], v[26:27], v[202:203], v[64:65]
	v_pk_fma_f32 v[68:69], v[26:27], v[218:219], v[68:69]
	v_pk_fma_f32 v[64:65], v[28:29], v[204:205], v[64:65]
	v_pk_fma_f32 v[68:69], v[28:29], v[220:221], v[68:69]
	v_pk_fma_f32 v[64:65], v[30:31], v[206:207], v[64:65]
	v_pk_fma_f32 v[68:69], v[30:31], v[222:223], v[68:69]
	v_pk_fma_f32 v[66:67], v[48:49], v[192:193], v[66:67]
	v_pk_fma_f32 v[70:71], v[48:49], v[208:209], v[70:71]
	v_pk_fma_f32 v[66:67], v[50:51], v[194:195], v[66:67]
	v_pk_fma_f32 v[70:71], v[50:51], v[210:211], v[70:71]
	v_pk_fma_f32 v[66:67], v[52:53], v[196:197], v[66:67]
	v_pk_fma_f32 v[70:71], v[52:53], v[212:213], v[70:71]
	v_pk_fma_f32 v[66:67], v[54:55], v[198:199], v[66:67]
	v_pk_fma_f32 v[70:71], v[54:55], v[214:215], v[70:71]
	v_pk_fma_f32 v[66:67], v[56:57], v[200:201], v[66:67]
	v_pk_fma_f32 v[70:71], v[56:57], v[216:217], v[70:71]
	v_pk_fma_f32 v[66:67], v[58:59], v[202:203], v[66:67]
	v_pk_fma_f32 v[70:71], v[58:59], v[218:219], v[70:71]
	v_pk_fma_f32 v[66:67], v[60:61], v[204:205], v[66:67]
	v_pk_fma_f32 v[70:71], v[60:61], v[220:221], v[70:71]
	v_pk_fma_f32 v[66:67], v[62:63], v[206:207], v[66:67]
	v_pk_fma_f32 v[70:71], v[62:63], v[222:223], v[70:71]
	ds_read_b32 v249, v251 offset:0
	ds_read_b32 v250, v251 offset:128
	v_lshlrev_b32_e32 v240, 16, v227
	v_lshlrev_b32_e32 v241, 16, v228
	s_waitcnt lgkmcnt(0)
	v_mul_f32_e32 v240, v240, v249
	v_mul_f32_e32 v241, v241, v250
	v_add_f32_e32 v68, v68, v69
	v_add_f32_e32 v70, v70, v71
	v_add_f32_e32 v64, v64, v65
	v_add_f32_e32 v66, v66, v67
	v_lshlrev_b32_e32 v245, 16, v229
	v_permlane32_swap_b32_e32 v68, v70
	v_permlane32_swap_b32_e32 v64, v66
	v_add_f32_e32 v244, v68, v70
	v_add_f32_e32 v64, v64, v66
	v_bfe_u32 v66, v64, 16, 1
	v_add3_u32 v66, v64, v66, s69
	v_permlane32_swap_b32_e32 v244, v245
	global_store_short_d16_hi v72, v66, s[22:23] offset:-4096
	v_add_u32_e32 v72, 0x400, v72
	v_lshl_add_u64 v[74:75], v[74:75], 0, s[54:55]
	s_branch .Lscan_v_s3e
; template <bool ID> __device__ __forceinline__ void rwkv_scan(const bf16_t* __restrict__ R, const bf16_t* __restrict__ EW, const bf16_t* __restrict__ K, const bf16_t* __restrict__ V, ...
;     ...
;     for (int s = 0; s < nsteps; ++s) {
;         L[lane] = bf2f(q2[4]); L[64 + lane] = __expf(-bf2f(q1[1])); L[128 + lane] = bf2f(q1[5]); L[192 + lane] = bf2f(q1[2]); L[256 + lane] = bf2f(q1[0]);
;         const float v = bf2f(q1[3]);
; #pragma unroll
;         for (int j = 0; j < 6; ++j) q1[j] = q2[j];
;         { const unsigned o = base + (unsigned)(s + 2 < nsteps ? s + 2 : nsteps - 1) * 512u; q2[0] = R[o]; q2[1] = EW[o]; q2[2] = K[o]; q2[3] = V[o]; q2[4] = A[o]; q2[5] = B[o]; }
;         const f2 sav2 = {sav, sav}, sai2 = {sai, sai}, v2 = {v, v};
;         f2 yv = {0.f, 0.f}, yi = {0.f, 0.f}, yv1 = {0.f, 0.f}, yi1 = {0.f, 0.f}, nv = {0.f, 0.f}, ni = {0.f, 0.f}, nv1 = {0.f, 0.f}, ni1 = {0.f, 0.f};
;         f32x4 ca = pa[0], cw = pa[16], cb = pa[32], ck = pa[48], cr = pa[64];
; #pragma unroll
;         for (int q = 0; q < 16; ++q) {
;             const f32x4 a4 = ca, w4 = cw, b4 = cb, k4 = ck, r4 = cr;
;             if (q < 15) { ca = pa[1 + q]; cw = pa[17 + q]; cb = pa[33 + q]; ck = pa[49 + q]; cr = pa[65 + q]; }
;             __builtin_amdgcn_sched_barrier(0);
;             { const f2 a2 = {a4[0], a4[1]}, w2 = {w4[0], w4[1]}, b2 = {b4[0], b4[1]}, k2 = {k4[0], k4[1]}, r2 = {r4[0], r4[1]};
;               f2 tv = sav2 * b2; tv = pfma(v2, k2, tv); Sv[2 * q] = pfma(Sv[2 * q], w2, tv); yv = pfma(Sv[2 * q], r2, yv); nv = pfma(Sv[2 * q], a2, nv);
;               if (ID) { const f2 ti = sai2 * b2; Si[2 * q] = pfma(Si[2 * q], w2, ti); yi = pfma(Si[2 * q], r2, yi); ni = pfma(Si[2 * q], a2, ni); } }
;             { const f2 a2 = {a4[2], a4[3]}, w2 = {w4[2], w4[3]}, b2 = {b4[2], b4[3]}, k2 = {k4[2], k4[3]}, r2 = {r4[2], r4[3]};
;               f2 tv = sav2 * b2; tv = pfma(v2, k2, tv); Sv[2 * q + 1] = pfma(Sv[2 * q + 1], w2, tv); yv1 = pfma(Sv[2 * q + 1], r2, yv1); nv1 = pfma(Sv[2 * q + 1], a2, nv1);
;               if (ID) { const f2 ti = sai2 * b2; Si[2 * q + 1] = pfma(Si[2 * q + 1], w2, ti); yi1 = pfma(Si[2 * q + 1], r2, yi1); ni1 = pfma(Si[2 * q + 1], a2, ni1); } }
;         }
;         sav = (nv[0] + nv[1]) + (nv1[0] + nv1[1]); sai = (ni[0] + ni[1]) + (ni1[0] + ni1[1]);
;         const unsigned cbo = base + (unsigned)s * 512u;
.Lscan_v_s3x:
	ds_read_b128 v[148:151], v76 offset:1024
	ds_read_b128 v[152:155], v76 offset:1056
	ds_read_b128 v[156:159], v76 offset:1088
	ds_read_b128 v[160:163], v76 offset:1120
	ds_read_b128 v[164:167], v76 offset:1280
	ds_read_b128 v[168:171], v76 offset:1312
	ds_read_b128 v[172:175], v76 offset:1344
	ds_read_b128 v[176:179], v76 offset:1376
	global_load_ushort v88, v72, s[4:5] offset:0
	global_load_ushort v89, v72, s[0:1] offset:0
	global_load_ushort v90, v72, s[12:13] offset:1024
	global_load_ushort v91, v[74:75], off offset:0
	global_load_ushort v92, v[74:75], off offset:64
	global_load_ushort v93, v72, s[2:3] offset:0
	v_mfma_f32_32x32x2_f32 v[0:15], v240, v244, v[0:15]
	v_mfma_f32_32x32x2_f32 v[32:47], v240, v245, v[32:47]
	ds_read_b128 v[192:195], v76 offset:1152
	ds_read_b128 v[196:199], v76 offset:1184
	ds_read_b128 v[200:203], v76 offset:1216
	ds_read_b128 v[204:207], v76 offset:1248
	ds_read_b128 v[208:211], v76 offset:1408
	ds_read_b128 v[212:215], v76 offset:1440
	ds_read_b128 v[216:219], v76 offset:1472
	ds_read_b128 v[220:223], v76 offset:1504
	v_mfma_f32_32x32x2_f32 v[16:31], v241, v244, v[16:31]
	v_mfma_f32_32x32x2_f32 v[48:63], v241, v245, v[48:63]
	s_waitcnt vmcnt(21)
	s_waitcnt lgkmcnt(8)
	s_nop 4
	v_pk_mul_f32 v[64:65], v[0:1], v[148:149]
	v_pk_mul_f32 v[68:69], v[0:1], v[164:165]
	v_pk_fma_f32 v[64:65], v[2:3], v[150:151], v[64:65]
	v_pk_fma_f32 v[68:69], v[2:3], v[166:167], v[68:69]
	v_pk_fma_f32 v[64:65], v[4:5], v[152:153], v[64:65]
	v_pk_fma_f32 v[68:69], v[4:5], v[168:169], v[68:69]
	v_pk_fma_f32 v[64:65], v[6:7], v[154:155], v[64:65]
	v_pk_fma_f32 v[68:69], v[6:7], v[170:171], v[68:69]
	v_pk_fma_f32 v[64:65], v[8:9], v[156:157], v[64:65]
	v_pk_fma_f32 v[68:69], v[8:9], v[172:173], v[68:69]
	v_pk_fma_f32 v[64:65], v[10:11], v[158:159], v[64:65]
	v_pk_fma_f32 v[68:69], v[10:11], v[174:175], v[68:69]
	v_pk_fma_f32 v[64:65], v[12:13], v[160:161], v[64:65]
	v_pk_fma_f32 v[68:69], v[12:13], v[176:177], v[68:69]
	v_pk_fma_f32 v[64:65], v[14:15], v[162:163], v[64:65]
	v_pk_fma_f32 v[68:69], v[14:15], v[178:179], v[68:69]
	v_pk_mul_f32 v[66:67], v[32:33], v[148:149]
	v_pk_mul_f32 v[70:71], v[32:33], v[164:165]
	v_pk_fma_f32 v[66:67], v[34:35], v[150:151], v[66:67]
	v_pk_fma_f32 v[70:71], v[34:35], v[166:167], v[70:71]
	v_pk_fma_f32 v[66:67], v[36:37], v[152:153], v[66:67]
	v_pk_fma_f32 v[70:71], v[36:37], v[168:169], v[70:71]
	v_pk_fma_f32 v[66:67], v[38:39], v[154:155], v[66:67]
	v_pk_fma_f32 v[70:71], v[38:39], v[170:171], v[70:71]
	v_pk_fma_f32 v[66:67], v[40:41], v[156:157], v[66:67]
	v_pk_fma_f32 v[70:71], v[40:41], v[172:173], v[70:71]
	v_pk_fma_f32 v[66:67], v[42:43], v[158:159], v[66:67]
	v_pk_fma_f32 v[70:71], v[42:43], v[174:175], v[70:71]
	v_pk_fma_f32 v[66:67], v[44:45], v[160:161], v[66:67]
	v_pk_fma_f32 v[70:71], v[44:45], v[176:177], v[70:71]
	v_pk_fma_f32 v[66:67], v[46:47], v[162:163], v[66:67]
	v_pk_fma_f32 v[70:71], v[46:47], v[178:179], v[70:71]
	s_waitcnt lgkmcnt(0)
	v_pk_fma_f32 v[64:65], v[16:17], v[192:193], v[64:65]
	v_pk_fma_f32 v[68:69], v[16:17], v[208:209], v[68:69]
	v_pk_fma_f32 v[64:65], v[18:19], v[194:195], v[64:65]
	v_pk_fma_f32 v[68:69], v[18:19], v[210:211], v[68:69]
	v_pk_fma_f32 v[64:65], v[20:21], v[196:197], v[64:65]
	v_pk_fma_f32 v[68:69], v[20:21], v[212:213], v[68:69]
	v_pk_fma_f32 v[64:65], v[22:23], v[198:199], v[64:65]
	v_pk_fma_f32 v[68:69], v[22:23], v[214:215], v[68:69]
	v_pk_fma_f32 v[64:65], v[24:25], v[200:201], v[64:65]
	v_pk_fma_f32 v[68:69], v[24:25], v[216:217], v[68:69]
	v_pk_fma_f32 v[64:65], v[26:27], v[202:203], v[64:65]
	v_pk_fma_f32 v[68:69], v[26:27], v[218:219], v[68:69]
	v_pk_fma_f32 v[64:65], v[28:29], v[204:205], v[64:65]
	v_pk_fma_f32 v[68:69], v[28:29], v[220:221], v[68:69]
	v_pk_fma_f32 v[64:65], v[30:31], v[206:207], v[64:65]
	v_pk_fma_f32 v[68:69], v[30:31], v[222:223], v[68:69]
	v_pk_fma_f32 v[66:67], v[48:49], v[192:193], v[66:67]
	v_pk_fma_f32 v[70:71], v[48:49], v[208:209], v[70:71]
	v_pk_fma_f32 v[66:67], v[50:51], v[194:195], v[66:67]
	v_pk_fma_f32 v[70:71], v[50:51], v[210:211], v[70:71]
	v_pk_fma_f32 v[66:67], v[52:53], v[196:197], v[66:67]
	v_pk_fma_f32 v[70:71], v[52:53], v[212:213], v[70:71]
	v_pk_fma_f32 v[66:67], v[54:55], v[198:199], v[66:67]
	v_pk_fma_f32 v[70:71], v[54:55], v[214:215], v[70:71]
	v_pk_fma_f32 v[66:67], v[56:57], v[200:201], v[66:67]
	v_pk_fma_f32 v[70:71], v[56:57], v[216:217], v[70:71]
	v_pk_fma_f32 v[66:67], v[58:59], v[202:203], v[66:67]
	v_pk_fma_f32 v[70:71], v[58:59], v[218:219], v[70:71]
	v_pk_fma_f32 v[66:67], v[60:61], v[204:205], v[66:67]
	v_pk_fma_f32 v[70:71], v[60:61], v[220:221], v[70:71]
	v_pk_fma_f32 v[66:67], v[62:63], v[206:207], v[66:67]
	v_pk_fma_f32 v[70:71], v[62:63], v[222:223], v[70:71]
	v_add_f32_e32 v68, v68, v69
	v_add_f32_e32 v70, v70, v71
	v_add_f32_e32 v64, v64, v65
	v_add_f32_e32 v66, v66, v67
	v_lshlrev_b32_e32 v245, 16, v229
	v_permlane32_swap_b32_e32 v68, v70
	v_permlane32_swap_b32_e32 v64, v66
	v_add_f32_e32 v244, v68, v70
	v_add_f32_e32 v64, v64, v66
	v_bfe_u32 v66, v64, 16, 1
	v_add3_u32 v66, v64, v66, s69
	v_permlane32_swap_b32_e32 v244, v245
	global_store_short_d16_hi v72, v66, s[22:23] offset:-4096
	ds_write_b32 v77, v246 offset:0
	ds_read_b128 v[148:151], v76 offset:0
	ds_read_b128 v[152:155], v76 offset:32
	ds_read_b128 v[156:159], v76 offset:64
	ds_read_b128 v[160:163], v76 offset:96
	ds_read_b128 v[164:167], v76 offset:128
	ds_read_b128 v[168:171], v76 offset:160
	ds_read_b128 v[172:175], v76 offset:192
	ds_read_b128 v[176:179], v76 offset:224
	s_waitcnt lgkmcnt(0)
; template <bool ID> __device__ __forceinline__ void rwkv_scan(const bf16_t* __restrict__ R, const bf16_t* __restrict__ EW, const bf16_t* __restrict__ K, const bf16_t* __restrict__ V, ...
;     ...
;     for (int s = 0; s < nsteps; ++s) {
;         L[lane] = bf2f(q2[4]); L[64 + lane] = __expf(-bf2f(q1[1])); L[128 + lane] = bf2f(q1[5]); L[192 + lane] = bf2f(q1[2]); L[256 + lane] = bf2f(q1[0]);
;         const float v = bf2f(q1[3]);
; #pragma unroll
;         for (int j = 0; j < 6; ++j) q1[j] = q2[j];
;         { const unsigned o = base + (unsigned)(s + 2 < nsteps ? s + 2 : nsteps - 1) * 512u; q2[0] = R[o]; q2[1] = EW[o]; q2[2] = K[o]; q2[3] = V[o]; q2[4] = A[o]; q2[5] = B[o]; }
;         const f2 sav2 = {sav, sav}, sai2 = {sai, sai}, v2 = {v, v};
;         f2 yv = {0.f, 0.f}, yi = {0.f, 0.f}, yv1 = {0.f, 0.f}, yi1 = {0.f, 0.f}, nv = {0.f, 0.f}, ni = {0.f, 0.f}, nv1 = {0.f, 0.f}, ni1 = {0.f, 0.f};
;         f32x4 ca = pa[0], cw = pa[16], cb = pa[32], ck = pa[48], cr = pa[64];
; #pragma unroll
;         for (int q = 0; q < 16; ++q) {
;             const f32x4 a4 = ca, w4 = cw, b4 = cb, k4 = ck, r4 = cr;
;             if (q < 15) { ca = pa[1 + q]; cw = pa[17 + q]; cb = pa[33 + q]; ck = pa[49 + q]; cr = pa[65 + q]; }
;             __builtin_amdgcn_sched_barrier(0);
;             { const f2 a2 = {a4[0], a4[1]}, w2 = {w4[0], w4[1]}, b2 = {b4[0], b4[1]}, k2 = {k4[0], k4[1]}, r2 = {r4[0], r4[1]};
;               f2 tv = sav2 * b2; tv = pfma(v2, k2, tv); Sv[2 * q] = pfma(Sv[2 * q], w2, tv); yv = pfma(Sv[2 * q], r2, yv); nv = pfma(Sv[2 * q], a2, nv);
;               if (ID) { const f2 ti = sai2 * b2; Si[2 * q] = pfma(Si[2 * q], w2, ti); yi = pfma(Si[2 * q], r2, yi); ni = pfma(Si[2 * q], a2, ni); } }
;             { const f2 a2 = {a4[2], a4[3]}, w2 = {w4[2], w4[3]}, b2 = {b4[2], b4[3]}, k2 = {k4[2], k4[3]}, r2 = {r4[2], r4[3]};
;               f2 tv = sav2 * b2; tv = pfma(v2, k2, tv); Sv[2 * q + 1] = pfma(Sv[2 * q + 1], w2, tv); yv1 = pfma(Sv[2 * q + 1], r2, yv1); nv1 = pfma(Sv[2 * q + 1], a2, nv1);
;               if (ID) { const f2 ti = sai2 * b2; Si[2 * q + 1] = pfma(Si[2 * q + 1], w2, ti); yi1 = pfma(Si[2 * q + 1], r2, yi1); ni1 = pfma(Si[2 * q + 1], a2, ni1); } }
;         }
;         sav = (nv[0] + nv[1]) + (nv1[0] + nv1[1]); sai = (ni[0] + ni[1]) + (ni1[0] + ni1[1]);
;         const unsigned cbo = base + (unsigned)s * 512u;
	v_pk_mul_f32 v[0:1], v[0:1], v[148:149]
	v_pk_mul_f32 v[2:3], v[2:3], v[150:151]
	v_pk_mul_f32 v[4:5], v[4:5], v[152:153]
	v_pk_mul_f32 v[6:7], v[6:7], v[154:155]
	v_pk_mul_f32 v[8:9], v[8:9], v[156:157]
	v_pk_mul_f32 v[10:11], v[10:11], v[158:159]
	v_pk_mul_f32 v[12:13], v[12:13], v[160:161]
	v_pk_mul_f32 v[14:15], v[14:15], v[162:163]
	v_pk_mul_f32 v[16:17], v[16:17], v[164:165]
	v_pk_mul_f32 v[18:19], v[18:19], v[166:167]
	v_pk_mul_f32 v[20:21], v[20:21], v[168:169]
	v_pk_mul_f32 v[22:23], v[22:23], v[170:171]
	v_pk_mul_f32 v[24:25], v[24:25], v[172:173]
	v_pk_mul_f32 v[26:27], v[26:27], v[174:175]
	v_pk_mul_f32 v[28:29], v[28:29], v[176:177]
	v_pk_mul_f32 v[30:31], v[30:31], v[178:179]
	v_pk_mul_f32 v[32:33], v[32:33], v[148:149]
	v_pk_mul_f32 v[34:35], v[34:35], v[150:151]
	v_pk_mul_f32 v[36:37], v[36:37], v[152:153]
	v_pk_mul_f32 v[38:39], v[38:39], v[154:155]
	v_pk_mul_f32 v[40:41], v[40:41], v[156:157]
	v_pk_mul_f32 v[42:43], v[42:43], v[158:159]
	v_pk_mul_f32 v[44:45], v[44:45], v[160:161]
	v_pk_mul_f32 v[46:47], v[46:47], v[162:163]
	v_pk_mul_f32 v[48:49], v[48:49], v[164:165]
	v_pk_mul_f32 v[50:51], v[50:51], v[166:167]
	v_pk_mul_f32 v[52:53], v[52:53], v[168:169]
	v_pk_mul_f32 v[54:55], v[54:55], v[170:171]
	v_pk_mul_f32 v[56:57], v[56:57], v[172:173]
	v_pk_mul_f32 v[58:59], v[58:59], v[174:175]
	v_pk_mul_f32 v[60:61], v[60:61], v[176:177]
	v_pk_mul_f32 v[62:63], v[62:63], v[178:179]
	v_mov_b32_e32 v246, 1.0
	v_lshlrev_b32_e32 v78, 16, v224
	v_mul_f32_e32 v78, 0xbfb8aa3b, v78
	v_exp_f32_e32 v78, v78
	v_lshlrev_b32_e32 v79, 16, v225
	v_lshlrev_b32_e32 v80, 16, v226
	v_mul_f32_e32 v246, v246, v78
	v_mul_f32_e32 v79, v79, v246
	v_mul_f32_e32 v80, v80, v246
	v_rcp_f32_e32 v248, v246
	s_nop 0
	ds_write2st64_b32 v77, v248, v79 offset0:0 offset1:1
	ds_write_b32 v77, v80 offset:512
	ds_read_b32 v249, v251 offset:0
	ds_read_b32 v250, v251 offset:128
	v_lshlrev_b32_e32 v240, 16, v227
	v_lshlrev_b32_e32 v241, 16, v228
	s_waitcnt lgkmcnt(0)
	v_mul_f32_e32 v240, v240, v249
	v_mul_f32_e32 v241, v241, v250
	s_waitcnt lgkmcnt(0)
	v_add_u32_e32 v72, 0x400, v72
	v_lshl_add_u64 v[74:75], v[74:75], 0, s[54:55]
.Lscan_v_s3e:
	s_add_i32 s41, s41, 1
	s_cmpk_lg_i32 s41, 32
	s_cbranch_scc1 .Lscan_v_loop
	s_waitcnt vmcnt(0) lgkmcnt(0)
	s_ashr_i32 s15, s36, 31
	s_mov_b32 s14, s36
	s_lshl_b64 s[14:15], s[14:15], 14
	s_add_u32 s14, s39, s14
	s_addc_u32 s15, s40, s15
	v_and_b32_e32 v79, 31, v139
	v_lshrrev_b32_e32 v78, 5, v139
	v_lshlrev_b32_e32 v79, 8, v79
	v_lshl_add_u32 v79, v78, 4, v79
	v_add_u32_e32 v80, 0x2000, v79
	global_store_dwordx4 v79, v[0:3], s[14:15] offset:0
	global_store_dwordx4 v79, v[4:7], s[14:15] offset:32
	global_store_dwordx4 v79, v[8:11], s[14:15] offset:64
	global_store_dwordx4 v79, v[12:15], s[14:15] offset:96
	global_store_dwordx4 v79, v[16:19], s[14:15] offset:128
	global_store_dwordx4 v79, v[20:23], s[14:15] offset:160
	global_store_dwordx4 v79, v[24:27], s[14:15] offset:192
	global_store_dwordx4 v79, v[28:31], s[14:15] offset:224
	global_store_dwordx4 v80, v[32:35], s[14:15] offset:0
	global_store_dwordx4 v80, v[36:39], s[14:15] offset:32
	global_store_dwordx4 v80, v[40:43], s[14:15] offset:64
	global_store_dwordx4 v80, v[44:47], s[14:15] offset:96
	global_store_dwordx4 v80, v[48:51], s[14:15] offset:128
	global_store_dwordx4 v80, v[52:55], s[14:15] offset:160
	global_store_dwordx4 v80, v[56:59], s[14:15] offset:192
	global_store_dwordx4 v80, v[60:63], s[14:15] offset:224
	s_branch .Lscan_tail
.Lscan_i:
	v_lshrrev_b32_e32 v78, 5, v139
	v_and_b32_e32 v79, 31, v139
	s_mov_b32 s26, -1
	s_mov_b32 s27, 0
	s_lshl_b32 s14, s36, 13
	s_and_b32 s14, s14, 0xffff0000
	s_lshl_b32 s15, s36, 6
	s_and_b32 s15, s15, 0x1c0
	s_or_b32 s14, s14, s15
	v_add_lshl_u32 v72, s14, v139, 1
	v_add_lshl_u32 v81, s14, v79, 1
	v_mov_b32_e32 v74, s20
	v_mov_b32_e32 v75, s21
	v_mov_b32_e32 v80, s6
	v_cndmask_b32_e64 v74, v80, v74, s[26:27]
	v_mov_b32_e32 v80, s7
	v_cndmask_b32_e64 v75, v80, v75, s[26:27]
	v_add_co_u32_e32 v74, vcc, v74, v81
	s_nop 1
	v_addc_co_u32_e32 v75, vcc, 0, v75, vcc
	v_lshl_add_u32 v76, v78, 4, s10
	v_lshl_add_u32 v77, v139, 2, s10
	v_lshl_add_u32 v251, v79, 2, s10
	v_mov_b32_e32 v246, 1.0
	v_lshlrev_b32_e32 v81, 2, v78
	v_sub_u32_e32 v81, v79, v81
	global_load_ushort v244, v72, s[12:13]
	global_load_ushort v224, v72, s[4:5] offset:0
	global_load_ushort v225, v72, s[0:1] offset:0
	global_load_ushort v226, v72, s[12:13] offset:1024
	global_load_ushort v227, v[74:75], off offset:0
	global_load_ushort v228, v[74:75], off offset:64
	global_load_ushort v230, v72, s[4:5] offset:1024
	global_load_ushort v231, v72, s[0:1] offset:1024
	global_load_ushort v232, v72, s[12:13] offset:2048
	global_load_ushort v233, v[74:75], off offset:1024
	global_load_ushort v234, v[74:75], off offset:1088
	global_load_ushort v82, v72, s[4:5] offset:2048
	global_load_ushort v83, v72, s[0:1] offset:2048
	global_load_ushort v84, v72, s[12:13] offset:3072
	global_load_ushort v85, v[74:75], off offset:2048
	global_load_ushort v86, v[74:75], off offset:2112
	v_add_u32_e32 v72, 0xc00, v72
	v_lshl_add_u64 v[74:75], v[74:75], 0, s[54:55]
	v_lshl_add_u64 v[74:75], v[74:75], 0, s[54:55]
	v_lshl_add_u64 v[74:75], v[74:75], 0, s[54:55]
	global_load_ushort v88, v72, s[4:5] offset:0
	global_load_ushort v89, v72, s[0:1] offset:0
	global_load_ushort v90, v72, s[12:13] offset:1024
	global_load_ushort v91, v[74:75], off offset:0
	global_load_ushort v92, v[74:75], off offset:64
	v_add_u32_e32 v72, 0x400, v72
	v_lshl_add_u64 v[74:75], v[74:75], 0, s[54:55]
	v_mov_b32_e32 v16, 0
	v_mov_b32_e32 v17, 0
	v_mov_b32_e32 v18, 0
	v_mov_b32_e32 v19, 0
	v_mov_b32_e32 v20, 0
	v_mov_b32_e32 v21, 0
; __device__ __forceinline__ int tidx() { int t = threadIdx.x; asm volatile("" : "+v"(t)); return t; }
; __device__ __forceinline__ float bf2f(unsigned short b) { return __uint_as_float((unsigned)b << 16); }
; template <bool ID> __device__ __forceinline__ void rwkv_scan(const bf16_t* __restrict__ R, const bf16_t* __restrict__ EW, const bf16_t* __restrict__ K, const bf16_t* __restrict__ V, ...
;     ...
;     for (int s = 0; s < nsteps; ++s) {
;         L[lane] = bf2f(q2[4]); L[64 + lane] = __expf(-bf2f(q1[1])); L[128 + lane] = bf2f(q1[5]); L[192 + lane] = bf2f(q1[2]); L[256 + lane] = bf2f(q1[0]);
;         const float v = bf2f(q1[3]);
; #pragma unroll
;         for (int j = 0; j < 6; ++j) q1[j] = q2[j];
;         { const unsigned o = base + (unsigned)(s + 2 < nsteps ? s + 2 : nsteps - 1) * 512u; q2[0] = R[o]; q2[1] = EW[o]; q2[2] = K[o]; q2[3] = V[o]; q2[4] = A[o]; q2[5] = B[o]; }
;         const f2 sav2 = {sav, sav}, sai2 = {sai, sai}, v2 = {v, v};
;         f2 yv = {0.f, 0.f}, yi = {0.f, 0.f}, yv1 = {0.f, 0.f}, yi1 = {0.f, 0.f}, nv = {0.f, 0.f}, ni = {0.f, 0.f}, nv1 = {0.f, 0.f}, ni1 = {0.f, 0.f};
;         f32x4 ca = pa[0], cw = pa[16], cb = pa[32], ck = pa[48], cr = pa[64];
; #pragma unroll
;         for (int q = 0; q < 16; ++q) {
;             const f32x4 a4 = ca, w4 = cw, b4 = cb, k4 = ck, r4 = cr;
;             if (q < 15) { ca = pa[1 + q]; cw = pa[17 + q]; cb = pa[33 + q]; ck = pa[49 + q]; cr = pa[65 + q]; }
;             __builtin_amdgcn_sched_barrier(0);
;             { const f2 a2 = {a4[0], a4[1]}, w2 = {w4[0], w4[1]}, b2 = {b4[0], b4[1]}, k2 = {k4[0], k4[1]}, r2 = {r4[0], r4[1]};
;               f2 tv = sav2 * b2; tv = pfma(v2, k2, tv); Sv[2 * q] = pfma(Sv[2 * q], w2, tv); yv = pfma(Sv[2 * q], r2, yv); nv = pfma(Sv[2 * q], a2, nv);
;               if (ID) { const f2 ti = sai2 * b2; Si[2 * q] = pfma(Si[2 * q], w2, ti); yi = pfma(Si[2 * q], r2, yi); ni = pfma(Si[2 * q], a2, ni); } }
; __device__ void phase_rwkv_scan(const Ctx& p, int l, LAS unsigned char* lds) {
;     ...
;             f2 Sv[32], Si[32]; const int li = tidx() & 63;
; #pragma unroll
;             for (int i = 0; i < 32; ++i) { Sv[i] = (f2){0.f, 0.f}; Si[i] = (f2){(2 * i == li) ? 1.f : 0.f, (2 * i + 1 == li) ? 1.f : 0.f}; }
;             rwkv_scan<true>(R, EW, K, V, A, B, (unsigned)((b * 8192 + c * 128) * 512 + h * 64 + lane), 128, Sv, Si, YH, QH, L, lane);
	v_mov_b32_e32 v22, 0
	v_mov_b32_e32 v23, 0
	v_mov_b32_e32 v24, 0
	v_mov_b32_e32 v25, 0
	v_mov_b32_e32 v26, 0
	v_mov_b32_e32 v27, 0
	v_mov_b32_e32 v28, 0
	v_mov_b32_e32 v29, 0
	v_mov_b32_e32 v30, 0
	v_mov_b32_e32 v31, 0
	v_mov_b32_e32 v32, 0
	v_mov_b32_e32 v33, 0
	v_mov_b32_e32 v34, 0
	v_mov_b32_e32 v35, 0
	v_mov_b32_e32 v36, 0
	v_mov_b32_e32 v37, 0
	v_mov_b32_e32 v38, 0
	v_mov_b32_e32 v39, 0
	v_mov_b32_e32 v40, 0
	v_mov_b32_e32 v41, 0
	v_mov_b32_e32 v42, 0
	v_mov_b32_e32 v43, 0
	v_mov_b32_e32 v44, 0
	v_mov_b32_e32 v45, 0
	v_mov_b32_e32 v46, 0
	v_mov_b32_e32 v47, 0
	v_cmp_eq_u32_e64 s[14:15], 0, v81
	s_nop 1
	v_cndmask_b32_e64 v0, 0, 1.0, s[14:15]
	v_cndmask_b32_e64 v48, 0, 1.0, s[14:15]
	v_cmp_eq_u32_e64 s[14:15], 1, v81
	s_nop 1
	v_cndmask_b32_e64 v1, 0, 1.0, s[14:15]
	v_cndmask_b32_e64 v49, 0, 1.0, s[14:15]
	v_cmp_eq_u32_e64 s[14:15], 2, v81
	s_nop 1
	v_cndmask_b32_e64 v2, 0, 1.0, s[14:15]
	v_cndmask_b32_e64 v50, 0, 1.0, s[14:15]
	v_cmp_eq_u32_e64 s[14:15], 3, v81
	s_nop 1
	v_cndmask_b32_e64 v3, 0, 1.0, s[14:15]
	v_cndmask_b32_e64 v51, 0, 1.0, s[14:15]
	v_cmp_eq_u32_e64 s[14:15], 8, v81
	s_nop 1
	v_cndmask_b32_e64 v4, 0, 1.0, s[14:15]
	v_cndmask_b32_e64 v52, 0, 1.0, s[14:15]
	v_cmp_eq_u32_e64 s[14:15], 9, v81
	s_nop 1
	v_cndmask_b32_e64 v5, 0, 1.0, s[14:15]
	v_cndmask_b32_e64 v53, 0, 1.0, s[14:15]
	v_cmp_eq_u32_e64 s[14:15], 10, v81
	s_nop 1
	v_cndmask_b32_e64 v6, 0, 1.0, s[14:15]
	v_cndmask_b32_e64 v54, 0, 1.0, s[14:15]
	v_cmp_eq_u32_e64 s[14:15], 11, v81
	s_nop 1
	v_cndmask_b32_e64 v7, 0, 1.0, s[14:15]
	v_cndmask_b32_e64 v55, 0, 1.0, s[14:15]
	v_cmp_eq_u32_e64 s[14:15], 16, v81
	s_nop 1
	v_cndmask_b32_e64 v8, 0, 1.0, s[14:15]
	v_cndmask_b32_e64 v56, 0, 1.0, s[14:15]
	v_cmp_eq_u32_e64 s[14:15], 17, v81
	s_nop 1
	v_cndmask_b32_e64 v9, 0, 1.0, s[14:15]
	v_cndmask_b32_e64 v57, 0, 1.0, s[14:15]
	v_cmp_eq_u32_e64 s[14:15], 18, v81
	s_nop 1
	v_cndmask_b32_e64 v10, 0, 1.0, s[14:15]
	v_cndmask_b32_e64 v58, 0, 1.0, s[14:15]
	v_cmp_eq_u32_e64 s[14:15], 19, v81
	s_nop 1
	v_cndmask_b32_e64 v11, 0, 1.0, s[14:15]
	v_cndmask_b32_e64 v59, 0, 1.0, s[14:15]
	v_cmp_eq_u32_e64 s[14:15], 24, v81
	s_nop 1
	v_cndmask_b32_e64 v12, 0, 1.0, s[14:15]
	v_cndmask_b32_e64 v60, 0, 1.0, s[14:15]
	v_cmp_eq_u32_e64 s[14:15], 25, v81
	s_nop 1
	v_cndmask_b32_e64 v13, 0, 1.0, s[14:15]
	v_cndmask_b32_e64 v61, 0, 1.0, s[14:15]
	v_cmp_eq_u32_e64 s[14:15], 26, v81
	s_nop 1
	v_cndmask_b32_e64 v14, 0, 1.0, s[14:15]
	v_cndmask_b32_e64 v62, 0, 1.0, s[14:15]
	v_cmp_eq_u32_e64 s[14:15], 27, v81
	s_nop 1
	v_cndmask_b32_e64 v15, 0, 1.0, s[14:15]
	v_cndmask_b32_e64 v63, 0, 1.0, s[14:15]
	s_waitcnt vmcnt(15)
	v_lshlrev_b32_e32 v78, 16, v224
	v_mul_f32_e32 v78, 0xbfb8aa3b, v78
	v_exp_f32_e32 v78, v78
	v_lshlrev_b32_e32 v79, 16, v225
	v_lshlrev_b32_e32 v80, 16, v226
	v_mul_f32_e32 v246, v246, v78
	v_mul_f32_e32 v79, v79, v246
	v_mul_f32_e32 v80, v80, v246
	v_rcp_f32_e32 v248, v246
	s_nop 0
	ds_write2st64_b32 v77, v248, v79 offset0:0 offset1:1
	ds_write_b32 v77, v80 offset:512
	ds_read_b32 v249, v251 offset:0
	ds_read_b32 v250, v251 offset:128
	v_lshlrev_b32_e32 v240, 16, v227
	v_lshlrev_b32_e32 v241, 16, v228
	s_waitcnt lgkmcnt(0)
	v_mul_f32_e32 v240, v240, v249
	v_mul_f32_e32 v241, v241, v250
	v_lshlrev_b32_e32 v244, 16, v244
	v_mov_b32_e32 v245, 0
	s_nop 0
	s_nop 0
	v_permlane32_swap_b32_e32 v244, v245
	s_movk_i32 s41, 0
.Lscan_i_loop:
	ds_read_b128 v[192:195], v76 offset:256
	ds_read_b128 v[196:199], v76 offset:288
	ds_read_b128 v[200:203], v76 offset:320
	ds_read_b128 v[204:207], v76 offset:352
	ds_read_b128 v[208:211], v76 offset:512
	ds_read_b128 v[212:215], v76 offset:544
	ds_read_b128 v[216:219], v76 offset:576
	ds_read_b128 v[220:223], v76 offset:608
	global_load_ushort v224, v72, s[4:5] offset:0
	global_load_ushort v225, v72, s[0:1] offset:0
	global_load_ushort v226, v72, s[12:13] offset:1024
	global_load_ushort v227, v[74:75], off offset:0
	global_load_ushort v228, v[74:75], off offset:64
	v_mfma_f32_32x32x2_f32 v[0:15], v240, v244, v[0:15]
	v_mfma_f32_32x32x2_f32 v[32:47], v240, v245, v[32:47]
	ds_read_b128 v[148:151], v76 offset:384
	ds_read_b128 v[152:155], v76 offset:416
	ds_read_b128 v[156:159], v76 offset:448
	ds_read_b128 v[160:163], v76 offset:480
	ds_read_b128 v[164:167], v76 offset:640
	ds_read_b128 v[168:171], v76 offset:672
	ds_read_b128 v[172:175], v76 offset:704
	ds_read_b128 v[176:179], v76 offset:736
	v_mfma_f32_32x32x2_f32 v[16:31], v241, v244, v[16:31]
	v_mfma_f32_32x32x2_f32 v[48:63], v241, v245, v[48:63]
	s_waitcnt vmcnt(15)
	v_lshlrev_b32_e32 v78, 16, v230
	v_mul_f32_e32 v78, 0xbfb8aa3b, v78
	v_exp_f32_e32 v78, v78
	v_lshlrev_b32_e32 v79, 16, v231
	v_lshlrev_b32_e32 v80, 16, v232
	v_mul_f32_e32 v246, v246, v78
	v_mul_f32_e32 v79, v79, v246
	v_mul_f32_e32 v80, v80, v246
	v_rcp_f32_e32 v248, v246
	s_nop 0
	ds_write2st64_b32 v77, v248, v79 offset0:3 offset1:4
	ds_write_b32 v77, v80 offset:1280
	s_waitcnt lgkmcnt(10)
; template <bool ID> __device__ __forceinline__ void rwkv_scan(const bf16_t* __restrict__ R, const bf16_t* __restrict__ EW, const bf16_t* __restrict__ K, const bf16_t* __restrict__ V, ...
;     ...
;         L[lane] = bf2f(q2[4]); L[64 + lane] = __expf(-bf2f(q1[1])); L[128 + lane] = bf2f(q1[5]); L[192 + lane] = bf2f(q1[2]); L[256 + lane] = bf2f(q1[0]);
;         const float v = bf2f(q1[3]);
; #pragma unroll
;         for (int j = 0; j < 6; ++j) q1[j] = q2[j];
;         { const unsigned o = base + (unsigned)(s + 2 < nsteps ? s + 2 : nsteps - 1) * 512u; q2[0] = R[o]; q2[1] = EW[o]; q2[2] = K[o]; q2[3] = V[o]; q2[4] = A[o]; q2[5] = B[o]; }
;         const f2 sav2 = {sav, sav}, sai2 = {sai, sai}, v2 = {v, v};
;         f2 yv = {0.f, 0.f}, yi = {0.f, 0.f}, yv1 = {0.f, 0.f}, yi1 = {0.f, 0.f}, nv = {0.f, 0.f}, ni = {0.f, 0.f}, nv1 = {0.f, 0.f}, ni1 = {0.f, 0.f};
;         f32x4 ca = pa[0], cw = pa[16], cb = pa[32], ck = pa[48], cr = pa[64];
; #pragma unroll
;         for (int q = 0; q < 16; ++q) {
;             const f32x4 a4 = ca, w4 = cw, b4 = cb, k4 = ck, r4 = cr;
;             if (q < 15) { ca = pa[1 + q]; cw = pa[17 + q]; cb = pa[33 + q]; ck = pa[49 + q]; cr = pa[65 + q]; }
;             __builtin_amdgcn_sched_barrier(0);
;             { const f2 a2 = {a4[0], a4[1]}, w2 = {w4[0], w4[1]}, b2 = {b4[0], b4[1]}, k2 = {k4[0], k4[1]}, r2 = {r4[0], r4[1]};
;               f2 tv = sav2 * b2; tv = pfma(v2, k2, tv); Sv[2 * q] = pfma(Sv[2 * q], w2, tv); yv = pfma(Sv[2 * q], r2, yv); nv = pfma(Sv[2 * q], a2, nv);
;               if (ID) { const f2 ti = sai2 * b2; Si[2 * q] = pfma(Si[2 * q], w2, ti); yi = pfma(Si[2 * q], r2, yi); ni = pfma(Si[2 * q], a2, ni); } }
;             { const f2 a2 = {a4[2], a4[3]}, w2 = {w4[2], w4[3]}, b2 = {b4[2], b4[3]}, k2 = {k4[2], k4[3]}, r2 = {r4[2], r4[3]};
;               f2 tv = sav2 * b2; tv = pfma(v2, k2, tv); Sv[2 * q + 1] = pfma(Sv[2 * q + 1], w2, tv); yv1 = pfma(Sv[2 * q + 1], r2, yv1); nv1 = pfma(Sv[2 * q + 1], a2, nv1);
;               if (ID) { const f2 ti = sai2 * b2; Si[2 * q + 1] = pfma(Si[2 * q + 1], w2, ti); yi1 = pfma(Si[2 * q + 1], r2, yi1); ni1 = pfma(Si[2 * q + 1], a2, ni1); } }
;         }
;         sav = (nv[0] + nv[1]) + (nv1[0] + nv1[1]); sai = (ni[0] + ni[1]) + (ni1[0] + ni1[1]);
;         const unsigned cbo = base + (unsigned)s * 512u;
	v_pk_mul_f32 v[64:65], v[0:1], v[192:193]
	v_pk_mul_f32 v[68:69], v[0:1], v[208:209]
	v_pk_fma_f32 v[64:65], v[2:3], v[194:195], v[64:65]
	v_pk_fma_f32 v[68:69], v[2:3], v[210:211], v[68:69]
	v_pk_fma_f32 v[64:65], v[4:5], v[196:197], v[64:65]
	v_pk_fma_f32 v[68:69], v[4:5], v[212:213], v[68:69]
	v_pk_fma_f32 v[64:65], v[6:7], v[198:199], v[64:65]
	v_pk_fma_f32 v[68:69], v[6:7], v[214:215], v[68:69]
	v_pk_fma_f32 v[64:65], v[8:9], v[200:201], v[64:65]
	v_pk_fma_f32 v[68:69], v[8:9], v[216:217], v[68:69]
	v_pk_fma_f32 v[64:65], v[10:11], v[202:203], v[64:65]
	v_pk_fma_f32 v[68:69], v[10:11], v[218:219], v[68:69]
	v_pk_fma_f32 v[64:65], v[12:13], v[204:205], v[64:65]
	v_pk_fma_f32 v[68:69], v[12:13], v[220:221], v[68:69]
	v_pk_fma_f32 v[64:65], v[14:15], v[206:207], v[64:65]
	v_pk_fma_f32 v[68:69], v[14:15], v[222:223], v[68:69]
	v_pk_mul_f32 v[66:67], v[32:33], v[192:193]
	v_pk_mul_f32 v[70:71], v[32:33], v[208:209]
	v_pk_fma_f32 v[66:67], v[34:35], v[194:195], v[66:67]
	v_pk_fma_f32 v[70:71], v[34:35], v[210:211], v[70:71]
	v_pk_fma_f32 v[66:67], v[36:37], v[196:197], v[66:67]
	v_pk_fma_f32 v[70:71], v[36:37], v[212:213], v[70:71]
	v_pk_fma_f32 v[66:67], v[38:39], v[198:199], v[66:67]
	v_pk_fma_f32 v[70:71], v[38:39], v[214:215], v[70:71]
	v_pk_fma_f32 v[66:67], v[40:41], v[200:201], v[66:67]
	v_pk_fma_f32 v[70:71], v[40:41], v[216:217], v[70:71]
	v_pk_fma_f32 v[66:67], v[42:43], v[202:203], v[66:67]
	v_pk_fma_f32 v[70:71], v[42:43], v[218:219], v[70:71]
	v_pk_fma_f32 v[66:67], v[44:45], v[204:205], v[66:67]
	v_pk_fma_f32 v[70:71], v[44:45], v[220:221], v[70:71]
	v_pk_fma_f32 v[66:67], v[46:47], v[206:207], v[66:67]
	v_pk_fma_f32 v[70:71], v[46:47], v[222:223], v[70:71]
	s_waitcnt lgkmcnt(2)
	v_pk_fma_f32 v[64:65], v[16:17], v[148:149], v[64:65]
	v_pk_fma_f32 v[68:69], v[16:17], v[164:165], v[68:69]
	v_pk_fma_f32 v[64:65], v[18:19], v[150:151], v[64:65]
	v_pk_fma_f32 v[68:69], v[18:19], v[166:167], v[68:69]
	v_pk_fma_f32 v[64:65], v[20:21], v[152:153], v[64:65]
	v_pk_fma_f32 v[68:69], v[20:21], v[168:169], v[68:69]
	v_pk_fma_f32 v[64:65], v[22:23], v[154:155], v[64:65]
	v_pk_fma_f32 v[68:69], v[22:23], v[170:171], v[68:69]
	v_pk_fma_f32 v[64:65], v[24:25], v[156:157], v[64:65]
	v_pk_fma_f32 v[68:69], v[24:25], v[172:173], v[68:69]
	v_pk_fma_f32 v[64:65], v[26:27], v[158:159], v[64:65]
	v_pk_fma_f32 v[68:69], v[26:27], v[174:175], v[68:69]
	v_pk_fma_f32 v[64:65], v[28:29], v[160:161], v[64:65]
	v_pk_fma_f32 v[68:69], v[28:29], v[176:177], v[68:69]
	v_pk_fma_f32 v[64:65], v[30:31], v[162:163], v[64:65]
	v_pk_fma_f32 v[68:69], v[30:31], v[178:179], v[68:69]
	v_pk_fma_f32 v[66:67], v[48:49], v[148:149], v[66:67]
	v_pk_fma_f32 v[70:71], v[48:49], v[164:165], v[70:71]
	v_pk_fma_f32 v[66:67], v[50:51], v[150:151], v[66:67]
	v_pk_fma_f32 v[70:71], v[50:51], v[166:167], v[70:71]
	v_pk_fma_f32 v[66:67], v[52:53], v[152:153], v[66:67]
	v_pk_fma_f32 v[70:71], v[52:53], v[168:169], v[70:71]
	v_pk_fma_f32 v[66:67], v[54:55], v[154:155], v[66:67]
	v_pk_fma_f32 v[70:71], v[54:55], v[170:171], v[70:71]
	v_pk_fma_f32 v[66:67], v[56:57], v[156:157], v[66:67]
	v_pk_fma_f32 v[70:71], v[56:57], v[172:173], v[70:71]
	v_pk_fma_f32 v[66:67], v[58:59], v[158:159], v[66:67]
	v_pk_fma_f32 v[70:71], v[58:59], v[174:175], v[70:71]
	v_pk_fma_f32 v[66:67], v[60:61], v[160:161], v[66:67]
	v_pk_fma_f32 v[70:71], v[60:61], v[176:177], v[70:71]
	v_pk_fma_f32 v[66:67], v[62:63], v[162:163], v[66:67]
	v_pk_fma_f32 v[70:71], v[62:63], v[178:179], v[70:71]
	ds_read_b32 v249, v251 offset:768
	ds_read_b32 v250, v251 offset:896
	v_lshlrev_b32_e32 v240, 16, v233
	v_lshlrev_b32_e32 v241, 16, v234
	s_waitcnt lgkmcnt(0)
	v_mul_f32_e32 v240, v240, v249
	v_mul_f32_e32 v241, v241, v250
	v_add_f32_e32 v68, v68, v69
	v_add_f32_e32 v70, v70, v71
	v_add_f32_e32 v64, v64, v65
	v_add_f32_e32 v66, v66, v67
	v_mov_b32_e32 v245, 0
	v_permlane32_swap_b32_e32 v68, v70
	v_permlane32_swap_b32_e32 v64, v66
	v_add_f32_e32 v244, v68, v70
	v_add_f32_e32 v64, v64, v66
	v_bfe_u32 v66, v64, 16, 1
	v_add3_u32 v66, v64, v66, s69
	v_permlane32_swap_b32_e32 v244, v245
	global_store_short_d16_hi v72, v66, s[24:25] offset:-4096
	v_add_u32_e32 v72, 0x400, v72
	v_lshl_add_u64 v[74:75], v[74:75], 0, s[54:55]
	ds_read_b128 v[148:151], v76 offset:1024
	ds_read_b128 v[152:155], v76 offset:1056
	ds_read_b128 v[156:159], v76 offset:1088
	ds_read_b128 v[160:163], v76 offset:1120
	ds_read_b128 v[164:167], v76 offset:1280
	ds_read_b128 v[168:171], v76 offset:1312
	ds_read_b128 v[172:175], v76 offset:1344
	ds_read_b128 v[176:179], v76 offset:1376
	global_load_ushort v230, v72, s[4:5] offset:0
	global_load_ushort v231, v72, s[0:1] offset:0
	global_load_ushort v232, v72, s[12:13] offset:1024
	global_load_ushort v233, v[74:75], off offset:0
	global_load_ushort v234, v[74:75], off offset:64
	v_mfma_f32_32x32x2_f32 v[0:15], v240, v244, v[0:15]
	v_mfma_f32_32x32x2_f32 v[32:47], v240, v245, v[32:47]
	ds_read_b128 v[192:195], v76 offset:1152
	ds_read_b128 v[196:199], v76 offset:1184
	ds_read_b128 v[200:203], v76 offset:1216
	ds_read_b128 v[204:207], v76 offset:1248
	ds_read_b128 v[208:211], v76 offset:1408
	ds_read_b128 v[212:215], v76 offset:1440
	ds_read_b128 v[216:219], v76 offset:1472
	ds_read_b128 v[220:223], v76 offset:1504
	v_mfma_f32_32x32x2_f32 v[16:31], v241, v244, v[16:31]
	v_mfma_f32_32x32x2_f32 v[48:63], v241, v245, v[48:63]
	s_waitcnt vmcnt(16)
	v_lshlrev_b32_e32 v78, 16, v82
	v_mul_f32_e32 v78, 0xbfb8aa3b, v78
	v_exp_f32_e32 v78, v78
	v_lshlrev_b32_e32 v79, 16, v83
	v_lshlrev_b32_e32 v80, 16, v84
	v_mul_f32_e32 v246, v246, v78
	v_mul_f32_e32 v79, v79, v246
	v_mul_f32_e32 v80, v80, v246
	v_rcp_f32_e32 v248, v246
	s_nop 0
	ds_write2st64_b32 v77, v248, v79 offset0:0 offset1:1
	ds_write_b32 v77, v80 offset:512
	s_waitcnt lgkmcnt(10)
; template <bool ID> __device__ __forceinline__ void rwkv_scan(const bf16_t* __restrict__ R, const bf16_t* __restrict__ EW, const bf16_t* __restrict__ K, const bf16_t* __restrict__ V, ...
;     ...
;         L[lane] = bf2f(q2[4]); L[64 + lane] = __expf(-bf2f(q1[1])); L[128 + lane] = bf2f(q1[5]); L[192 + lane] = bf2f(q1[2]); L[256 + lane] = bf2f(q1[0]);
;         const float v = bf2f(q1[3]);
; #pragma unroll
;         for (int j = 0; j < 6; ++j) q1[j] = q2[j];
;         { const unsigned o = base + (unsigned)(s + 2 < nsteps ? s + 2 : nsteps - 1) * 512u; q2[0] = R[o]; q2[1] = EW[o]; q2[2] = K[o]; q2[3] = V[o]; q2[4] = A[o]; q2[5] = B[o]; }
;         const f2 sav2 = {sav, sav}, sai2 = {sai, sai}, v2 = {v, v};
;         f2 yv = {0.f, 0.f}, yi = {0.f, 0.f}, yv1 = {0.f, 0.f}, yi1 = {0.f, 0.f}, nv = {0.f, 0.f}, ni = {0.f, 0.f}, nv1 = {0.f, 0.f}, ni1 = {0.f, 0.f};
;         f32x4 ca = pa[0], cw = pa[16], cb = pa[32], ck = pa[48], cr = pa[64];
; #pragma unroll
;         for (int q = 0; q < 16; ++q) {
;             const f32x4 a4 = ca, w4 = cw, b4 = cb, k4 = ck, r4 = cr;
;             if (q < 15) { ca = pa[1 + q]; cw = pa[17 + q]; cb = pa[33 + q]; ck = pa[49 + q]; cr = pa[65 + q]; }
;             __builtin_amdgcn_sched_barrier(0);
;             { const f2 a2 = {a4[0], a4[1]}, w2 = {w4[0], w4[1]}, b2 = {b4[0], b4[1]}, k2 = {k4[0], k4[1]}, r2 = {r4[0], r4[1]};
;               f2 tv = sav2 * b2; tv = pfma(v2, k2, tv); Sv[2 * q] = pfma(Sv[2 * q], w2, tv); yv = pfma(Sv[2 * q], r2, yv); nv = pfma(Sv[2 * q], a2, nv);
;               if (ID) { const f2 ti = sai2 * b2; Si[2 * q] = pfma(Si[2 * q], w2, ti); yi = pfma(Si[2 * q], r2, yi); ni = pfma(Si[2 * q], a2, ni); } }
;             { const f2 a2 = {a4[2], a4[3]}, w2 = {w4[2], w4[3]}, b2 = {b4[2], b4[3]}, k2 = {k4[2], k4[3]}, r2 = {r4[2], r4[3]};
;               f2 tv = sav2 * b2; tv = pfma(v2, k2, tv); Sv[2 * q + 1] = pfma(Sv[2 * q + 1], w2, tv); yv1 = pfma(Sv[2 * q + 1], r2, yv1); nv1 = pfma(Sv[2 * q + 1], a2, nv1);
;               if (ID) { const f2 ti = sai2 * b2; Si[2 * q + 1] = pfma(Si[2 * q + 1], w2, ti); yi1 = pfma(Si[2 * q + 1], r2, yi1); ni1 = pfma(Si[2 * q + 1], a2, ni1); } }
;         }
;         sav = (nv[0] + nv[1]) + (nv1[0] + nv1[1]); sai = (ni[0] + ni[1]) + (ni1[0] + ni1[1]);
;         const unsigned cbo = base + (unsigned)s * 512u;
	v_pk_mul_f32 v[64:65], v[0:1], v[148:149]
	v_pk_mul_f32 v[68:69], v[0:1], v[164:165]
	v_pk_fma_f32 v[64:65], v[2:3], v[150:151], v[64:65]
	v_pk_fma_f32 v[68:69], v[2:3], v[166:167], v[68:69]
	v_pk_fma_f32 v[64:65], v[4:5], v[152:153], v[64:65]
	v_pk_fma_f32 v[68:69], v[4:5], v[168:169], v[68:69]
	v_pk_fma_f32 v[64:65], v[6:7], v[154:155], v[64:65]
	v_pk_fma_f32 v[68:69], v[6:7], v[170:171], v[68:69]
	v_pk_fma_f32 v[64:65], v[8:9], v[156:157], v[64:65]
	v_pk_fma_f32 v[68:69], v[8:9], v[172:173], v[68:69]
	v_pk_fma_f32 v[64:65], v[10:11], v[158:159], v[64:65]
	v_pk_fma_f32 v[68:69], v[10:11], v[174:175], v[68:69]
	v_pk_fma_f32 v[64:65], v[12:13], v[160:161], v[64:65]
	v_pk_fma_f32 v[68:69], v[12:13], v[176:177], v[68:69]
	v_pk_fma_f32 v[64:65], v[14:15], v[162:163], v[64:65]
	v_pk_fma_f32 v[68:69], v[14:15], v[178:179], v[68:69]
	v_pk_mul_f32 v[66:67], v[32:33], v[148:149]
	v_pk_mul_f32 v[70:71], v[32:33], v[164:165]
	v_pk_fma_f32 v[66:67], v[34:35], v[150:151], v[66:67]
	v_pk_fma_f32 v[70:71], v[34:35], v[166:167], v[70:71]
	v_pk_fma_f32 v[66:67], v[36:37], v[152:153], v[66:67]
	v_pk_fma_f32 v[70:71], v[36:37], v[168:169], v[70:71]
	v_pk_fma_f32 v[66:67], v[38:39], v[154:155], v[66:67]
	v_pk_fma_f32 v[70:71], v[38:39], v[170:171], v[70:71]
	v_pk_fma_f32 v[66:67], v[40:41], v[156:157], v[66:67]
	v_pk_fma_f32 v[70:71], v[40:41], v[172:173], v[70:71]
	v_pk_fma_f32 v[66:67], v[42:43], v[158:159], v[66:67]
	v_pk_fma_f32 v[70:71], v[42:43], v[174:175], v[70:71]
	v_pk_fma_f32 v[66:67], v[44:45], v[160:161], v[66:67]
	v_pk_fma_f32 v[70:71], v[44:45], v[176:177], v[70:71]
	v_pk_fma_f32 v[66:67], v[46:47], v[162:163], v[66:67]
	v_pk_fma_f32 v[70:71], v[46:47], v[178:179], v[70:71]
	s_waitcnt lgkmcnt(2)
	v_pk_fma_f32 v[64:65], v[16:17], v[192:193], v[64:65]
	v_pk_fma_f32 v[68:69], v[16:17], v[208:209], v[68:69]
	v_pk_fma_f32 v[64:65], v[18:19], v[194:195], v[64:65]
	v_pk_fma_f32 v[68:69], v[18:19], v[210:211], v[68:69]
	v_pk_fma_f32 v[64:65], v[20:21], v[196:197], v[64:65]
	v_pk_fma_f32 v[68:69], v[20:21], v[212:213], v[68:69]
	v_pk_fma_f32 v[64:65], v[22:23], v[198:199], v[64:65]
	v_pk_fma_f32 v[68:69], v[22:23], v[214:215], v[68:69]
	v_pk_fma_f32 v[64:65], v[24:25], v[200:201], v[64:65]
	v_pk_fma_f32 v[68:69], v[24:25], v[216:217], v[68:69]
	v_pk_fma_f32 v[64:65], v[26:27], v[202:203], v[64:65]
	v_pk_fma_f32 v[68:69], v[26:27], v[218:219], v[68:69]
	v_pk_fma_f32 v[64:65], v[28:29], v[204:205], v[64:65]
	v_pk_fma_f32 v[68:69], v[28:29], v[220:221], v[68:69]
	v_pk_fma_f32 v[64:65], v[30:31], v[206:207], v[64:65]
	v_pk_fma_f32 v[68:69], v[30:31], v[222:223], v[68:69]
	v_pk_fma_f32 v[66:67], v[48:49], v[192:193], v[66:67]
	v_pk_fma_f32 v[70:71], v[48:49], v[208:209], v[70:71]
	v_pk_fma_f32 v[66:67], v[50:51], v[194:195], v[66:67]
	v_pk_fma_f32 v[70:71], v[50:51], v[210:211], v[70:71]
	v_pk_fma_f32 v[66:67], v[52:53], v[196:197], v[66:67]
	v_pk_fma_f32 v[70:71], v[52:53], v[212:213], v[70:71]
	v_pk_fma_f32 v[66:67], v[54:55], v[198:199], v[66:67]
	v_pk_fma_f32 v[70:71], v[54:55], v[214:215], v[70:71]
	v_pk_fma_f32 v[66:67], v[56:57], v[200:201], v[66:67]
	v_pk_fma_f32 v[70:71], v[56:57], v[216:217], v[70:71]
	v_pk_fma_f32 v[66:67], v[58:59], v[202:203], v[66:67]
	v_pk_fma_f32 v[70:71], v[58:59], v[218:219], v[70:71]
	v_pk_fma_f32 v[66:67], v[60:61], v[204:205], v[66:67]
	v_pk_fma_f32 v[70:71], v[60:61], v[220:221], v[70:71]
	v_pk_fma_f32 v[66:67], v[62:63], v[206:207], v[66:67]
	v_pk_fma_f32 v[70:71], v[62:63], v[222:223], v[70:71]
	ds_read_b32 v249, v251 offset:0
	ds_read_b32 v250, v251 offset:128
	v_lshlrev_b32_e32 v240, 16, v85
	v_lshlrev_b32_e32 v241, 16, v86
	s_waitcnt lgkmcnt(0)
	v_mul_f32_e32 v240, v240, v249
	v_mul_f32_e32 v241, v241, v250
	v_add_f32_e32 v68, v68, v69
	v_add_f32_e32 v70, v70, v71
	v_add_f32_e32 v64, v64, v65
	v_add_f32_e32 v66, v66, v67
	v_mov_b32_e32 v245, 0
	v_permlane32_swap_b32_e32 v68, v70
	v_permlane32_swap_b32_e32 v64, v66
	v_add_f32_e32 v244, v68, v70
	v_add_f32_e32 v64, v64, v66
	v_bfe_u32 v66, v64, 16, 1
	v_add3_u32 v66, v64, v66, s69
	v_permlane32_swap_b32_e32 v244, v245
	global_store_short_d16_hi v72, v66, s[24:25] offset:-4096
	v_add_u32_e32 v72, 0x400, v72
	v_lshl_add_u64 v[74:75], v[74:75], 0, s[54:55]
	ds_read_b128 v[192:195], v76 offset:256
	ds_read_b128 v[196:199], v76 offset:288
	ds_read_b128 v[200:203], v76 offset:320
	ds_read_b128 v[204:207], v76 offset:352
	ds_read_b128 v[208:211], v76 offset:512
	ds_read_b128 v[212:215], v76 offset:544
	ds_read_b128 v[216:219], v76 offset:576
	ds_read_b128 v[220:223], v76 offset:608
	global_load_ushort v82, v72, s[4:5] offset:0
	global_load_ushort v83, v72, s[0:1] offset:0
	global_load_ushort v84, v72, s[12:13] offset:1024
	global_load_ushort v85, v[74:75], off offset:0
	global_load_ushort v86, v[74:75], off offset:64
	v_mfma_f32_32x32x2_f32 v[0:15], v240, v244, v[0:15]
	v_mfma_f32_32x32x2_f32 v[32:47], v240, v245, v[32:47]
	ds_read_b128 v[148:151], v76 offset:384
	ds_read_b128 v[152:155], v76 offset:416
	ds_read_b128 v[156:159], v76 offset:448
	ds_read_b128 v[160:163], v76 offset:480
	ds_read_b128 v[164:167], v76 offset:640
	ds_read_b128 v[168:171], v76 offset:672
	ds_read_b128 v[172:175], v76 offset:704
	ds_read_b128 v[176:179], v76 offset:736
	v_mfma_f32_32x32x2_f32 v[16:31], v241, v244, v[16:31]
	v_mfma_f32_32x32x2_f32 v[48:63], v241, v245, v[48:63]
	s_waitcnt vmcnt(17)
	v_lshlrev_b32_e32 v78, 16, v88
	v_mul_f32_e32 v78, 0xbfb8aa3b, v78
	v_exp_f32_e32 v78, v78
	v_lshlrev_b32_e32 v79, 16, v89
	v_lshlrev_b32_e32 v80, 16, v90
	v_mul_f32_e32 v246, v246, v78
	v_mul_f32_e32 v79, v79, v246
	v_mul_f32_e32 v80, v80, v246
	v_rcp_f32_e32 v248, v246
	s_nop 0
	ds_write2st64_b32 v77, v248, v79 offset0:3 offset1:4
	ds_write_b32 v77, v80 offset:1280
	s_waitcnt lgkmcnt(10)
; template <bool ID> __device__ __forceinline__ void rwkv_scan(const bf16_t* __restrict__ R, const bf16_t* __restrict__ EW, const bf16_t* __restrict__ K, const bf16_t* __restrict__ V, ...
;     ...
;         L[lane] = bf2f(q2[4]); L[64 + lane] = __expf(-bf2f(q1[1])); L[128 + lane] = bf2f(q1[5]); L[192 + lane] = bf2f(q1[2]); L[256 + lane] = bf2f(q1[0]);
;         const float v = bf2f(q1[3]);
; #pragma unroll
;         for (int j = 0; j < 6; ++j) q1[j] = q2[j];
;         { const unsigned o = base + (unsigned)(s + 2 < nsteps ? s + 2 : nsteps - 1) * 512u; q2[0] = R[o]; q2[1] = EW[o]; q2[2] = K[o]; q2[3] = V[o]; q2[4] = A[o]; q2[5] = B[o]; }
;         const f2 sav2 = {sav, sav}, sai2 = {sai, sai}, v2 = {v, v};
;         f2 yv = {0.f, 0.f}, yi = {0.f, 0.f}, yv1 = {0.f, 0.f}, yi1 = {0.f, 0.f}, nv = {0.f, 0.f}, ni = {0.f, 0.f}, nv1 = {0.f, 0.f}, ni1 = {0.f, 0.f};
;         f32x4 ca = pa[0], cw = pa[16], cb = pa[32], ck = pa[48], cr = pa[64];
; #pragma unroll
;         for (int q = 0; q < 16; ++q) {
;             const f32x4 a4 = ca, w4 = cw, b4 = cb, k4 = ck, r4 = cr;
;             if (q < 15) { ca = pa[1 + q]; cw = pa[17 + q]; cb = pa[33 + q]; ck = pa[49 + q]; cr = pa[65 + q]; }
;             __builtin_amdgcn_sched_barrier(0);
;             { const f2 a2 = {a4[0], a4[1]}, w2 = {w4[0], w4[1]}, b2 = {b4[0], b4[1]}, k2 = {k4[0], k4[1]}, r2 = {r4[0], r4[1]};
;               f2 tv = sav2 * b2; tv = pfma(v2, k2, tv); Sv[2 * q] = pfma(Sv[2 * q], w2, tv); yv = pfma(Sv[2 * q], r2, yv); nv = pfma(Sv[2 * q], a2, nv);
;               if (ID) { const f2 ti = sai2 * b2; Si[2 * q] = pfma(Si[2 * q], w2, ti); yi = pfma(Si[2 * q], r2, yi); ni = pfma(Si[2 * q], a2, ni); } }
;             { const f2 a2 = {a4[2], a4[3]}, w2 = {w4[2], w4[3]}, b2 = {b4[2], b4[3]}, k2 = {k4[2], k4[3]}, r2 = {r4[2], r4[3]};
;               f2 tv = sav2 * b2; tv = pfma(v2, k2, tv); Sv[2 * q + 1] = pfma(Sv[2 * q + 1], w2, tv); yv1 = pfma(Sv[2 * q + 1], r2, yv1); nv1 = pfma(Sv[2 * q + 1], a2, nv1);
;               if (ID) { const f2 ti = sai2 * b2; Si[2 * q + 1] = pfma(Si[2 * q + 1], w2, ti); yi1 = pfma(Si[2 * q + 1], r2, yi1); ni1 = pfma(Si[2 * q + 1], a2, ni1); } }
;         }
;         sav = (nv[0] + nv[1]) + (nv1[0] + nv1[1]); sai = (ni[0] + ni[1]) + (ni1[0] + ni1[1]);
;         const unsigned cbo = base + (unsigned)s * 512u;
	v_pk_mul_f32 v[64:65], v[0:1], v[192:193]
	v_pk_mul_f32 v[68:69], v[0:1], v[208:209]
	v_pk_fma_f32 v[64:65], v[2:3], v[194:195], v[64:65]
	v_pk_fma_f32 v[68:69], v[2:3], v[210:211], v[68:69]
	v_pk_fma_f32 v[64:65], v[4:5], v[196:197], v[64:65]
	v_pk_fma_f32 v[68:69], v[4:5], v[212:213], v[68:69]
	v_pk_fma_f32 v[64:65], v[6:7], v[198:199], v[64:65]
	v_pk_fma_f32 v[68:69], v[6:7], v[214:215], v[68:69]
	v_pk_fma_f32 v[64:65], v[8:9], v[200:201], v[64:65]
	v_pk_fma_f32 v[68:69], v[8:9], v[216:217], v[68:69]
	v_pk_fma_f32 v[64:65], v[10:11], v[202:203], v[64:65]
	v_pk_fma_f32 v[68:69], v[10:11], v[218:219], v[68:69]
	v_pk_fma_f32 v[64:65], v[12:13], v[204:205], v[64:65]
	v_pk_fma_f32 v[68:69], v[12:13], v[220:221], v[68:69]
	v_pk_fma_f32 v[64:65], v[14:15], v[206:207], v[64:65]
	v_pk_fma_f32 v[68:69], v[14:15], v[222:223], v[68:69]
	v_pk_mul_f32 v[66:67], v[32:33], v[192:193]
	v_pk_mul_f32 v[70:71], v[32:33], v[208:209]
	v_pk_fma_f32 v[66:67], v[34:35], v[194:195], v[66:67]
	v_pk_fma_f32 v[70:71], v[34:35], v[210:211], v[70:71]
	v_pk_fma_f32 v[66:67], v[36:37], v[196:197], v[66:67]
	v_pk_fma_f32 v[70:71], v[36:37], v[212:213], v[70:71]
	v_pk_fma_f32 v[66:67], v[38:39], v[198:199], v[66:67]
	v_pk_fma_f32 v[70:71], v[38:39], v[214:215], v[70:71]
	v_pk_fma_f32 v[66:67], v[40:41], v[200:201], v[66:67]
	v_pk_fma_f32 v[70:71], v[40:41], v[216:217], v[70:71]
	v_pk_fma_f32 v[66:67], v[42:43], v[202:203], v[66:67]
	v_pk_fma_f32 v[70:71], v[42:43], v[218:219], v[70:71]
	v_pk_fma_f32 v[66:67], v[44:45], v[204:205], v[66:67]
	v_pk_fma_f32 v[70:71], v[44:45], v[220:221], v[70:71]
	v_pk_fma_f32 v[66:67], v[46:47], v[206:207], v[66:67]
	v_pk_fma_f32 v[70:71], v[46:47], v[222:223], v[70:71]
	s_waitcnt lgkmcnt(2)
	v_pk_fma_f32 v[64:65], v[16:17], v[148:149], v[64:65]
	v_pk_fma_f32 v[68:69], v[16:17], v[164:165], v[68:69]
	v_pk_fma_f32 v[64:65], v[18:19], v[150:151], v[64:65]
	v_pk_fma_f32 v[68:69], v[18:19], v[166:167], v[68:69]
	v_pk_fma_f32 v[64:65], v[20:21], v[152:153], v[64:65]
	v_pk_fma_f32 v[68:69], v[20:21], v[168:169], v[68:69]
	v_pk_fma_f32 v[64:65], v[22:23], v[154:155], v[64:65]
	v_pk_fma_f32 v[68:69], v[22:23], v[170:171], v[68:69]
	v_pk_fma_f32 v[64:65], v[24:25], v[156:157], v[64:65]
	v_pk_fma_f32 v[68:69], v[24:25], v[172:173], v[68:69]
	v_pk_fma_f32 v[64:65], v[26:27], v[158:159], v[64:65]
	v_pk_fma_f32 v[68:69], v[26:27], v[174:175], v[68:69]
	v_pk_fma_f32 v[64:65], v[28:29], v[160:161], v[64:65]
	v_pk_fma_f32 v[68:69], v[28:29], v[176:177], v[68:69]
	v_pk_fma_f32 v[64:65], v[30:31], v[162:163], v[64:65]
	v_pk_fma_f32 v[68:69], v[30:31], v[178:179], v[68:69]
	v_pk_fma_f32 v[66:67], v[48:49], v[148:149], v[66:67]
	v_pk_fma_f32 v[70:71], v[48:49], v[164:165], v[70:71]
	v_pk_fma_f32 v[66:67], v[50:51], v[150:151], v[66:67]
	v_pk_fma_f32 v[70:71], v[50:51], v[166:167], v[70:71]
	v_pk_fma_f32 v[66:67], v[52:53], v[152:153], v[66:67]
	v_pk_fma_f32 v[70:71], v[52:53], v[168:169], v[70:71]
	v_pk_fma_f32 v[66:67], v[54:55], v[154:155], v[66:67]
	v_pk_fma_f32 v[70:71], v[54:55], v[170:171], v[70:71]
	v_pk_fma_f32 v[66:67], v[56:57], v[156:157], v[66:67]
	v_pk_fma_f32 v[70:71], v[56:57], v[172:173], v[70:71]
	v_pk_fma_f32 v[66:67], v[58:59], v[158:159], v[66:67]
	v_pk_fma_f32 v[70:71], v[58:59], v[174:175], v[70:71]
	v_pk_fma_f32 v[66:67], v[60:61], v[160:161], v[66:67]
	v_pk_fma_f32 v[70:71], v[60:61], v[176:177], v[70:71]
	v_pk_fma_f32 v[66:67], v[62:63], v[162:163], v[66:67]
	v_pk_fma_f32 v[70:71], v[62:63], v[178:179], v[70:71]
	ds_read_b32 v249, v251 offset:768
	ds_read_b32 v250, v251 offset:896
	v_lshlrev_b32_e32 v240, 16, v91
	v_lshlrev_b32_e32 v241, 16, v92
	s_waitcnt lgkmcnt(0)
	v_mul_f32_e32 v240, v240, v249
	v_mul_f32_e32 v241, v241, v250
	v_add_f32_e32 v68, v68, v69
	v_add_f32_e32 v70, v70, v71
	v_add_f32_e32 v64, v64, v65
	v_add_f32_e32 v66, v66, v67
	v_mov_b32_e32 v245, 0
	v_permlane32_swap_b32_e32 v68, v70
	v_permlane32_swap_b32_e32 v64, v66
	v_add_f32_e32 v244, v68, v70
	v_add_f32_e32 v64, v64, v66
	v_bfe_u32 v66, v64, 16, 1
	v_add3_u32 v66, v64, v66, s69
	v_permlane32_swap_b32_e32 v244, v245
	global_store_short_d16_hi v72, v66, s[24:25] offset:-4096
	v_add_u32_e32 v72, 0x400, v72
	v_lshl_add_u64 v[74:75], v[74:75], 0, s[54:55]
	s_and_b32 s14, s41, 15
	s_cmp_eq_u32 s14, 15
	s_cbranch_scc1 .Lscan_i_s3x
; template <bool ID> __device__ __forceinline__ void rwkv_scan(const bf16_t* __restrict__ R, const bf16_t* __restrict__ EW, const bf16_t* __restrict__ K, const bf16_t* __restrict__ V, ...
;     ...
;         L[lane] = bf2f(q2[4]); L[64 + lane] = __expf(-bf2f(q1[1])); L[128 + lane] = bf2f(q1[5]); L[192 + lane] = bf2f(q1[2]); L[256 + lane] = bf2f(q1[0]);
;         const float v = bf2f(q1[3]);
; #pragma unroll
;         for (int j = 0; j < 6; ++j) q1[j] = q2[j];
;         { const unsigned o = base + (unsigned)(s + 2 < nsteps ? s + 2 : nsteps - 1) * 512u; q2[0] = R[o]; q2[1] = EW[o]; q2[2] = K[o]; q2[3] = V[o]; q2[4] = A[o]; q2[5] = B[o]; }
;         const f2 sav2 = {sav, sav}, sai2 = {sai, sai}, v2 = {v, v};
;         f2 yv = {0.f, 0.f}, yi = {0.f, 0.f}, yv1 = {0.f, 0.f}, yi1 = {0.f, 0.f}, nv = {0.f, 0.f}, ni = {0.f, 0.f}, nv1 = {0.f, 0.f}, ni1 = {0.f, 0.f};
;         f32x4 ca = pa[0], cw = pa[16], cb = pa[32], ck = pa[48], cr = pa[64];
; #pragma unroll
;         for (int q = 0; q < 16; ++q) {
;             const f32x4 a4 = ca, w4 = cw, b4 = cb, k4 = ck, r4 = cr;
;             if (q < 15) { ca = pa[1 + q]; cw = pa[17 + q]; cb = pa[33 + q]; ck = pa[49 + q]; cr = pa[65 + q]; }
;             __builtin_amdgcn_sched_barrier(0);
;             { const f2 a2 = {a4[0], a4[1]}, w2 = {w4[0], w4[1]}, b2 = {b4[0], b4[1]}, k2 = {k4[0], k4[1]}, r2 = {r4[0], r4[1]};
;               f2 tv = sav2 * b2; tv = pfma(v2, k2, tv); Sv[2 * q] = pfma(Sv[2 * q], w2, tv); yv = pfma(Sv[2 * q], r2, yv); nv = pfma(Sv[2 * q], a2, nv);
;               if (ID) { const f2 ti = sai2 * b2; Si[2 * q] = pfma(Si[2 * q], w2, ti); yi = pfma(Si[2 * q], r2, yi); ni = pfma(Si[2 * q], a2, ni); } }
;             { const f2 a2 = {a4[2], a4[3]}, w2 = {w4[2], w4[3]}, b2 = {b4[2], b4[3]}, k2 = {k4[2], k4[3]}, r2 = {r4[2], r4[3]};
;               f2 tv = sav2 * b2; tv = pfma(v2, k2, tv); Sv[2 * q + 1] = pfma(Sv[2 * q + 1], w2, tv); yv1 = pfma(Sv[2 * q + 1], r2, yv1); nv1 = pfma(Sv[2 * q + 1], a2, nv1);
;               if (ID) { const f2 ti = sai2 * b2; Si[2 * q + 1] = pfma(Si[2 * q + 1], w2, ti); yi1 = pfma(Si[2 * q + 1], r2, yi1); ni1 = pfma(Si[2 * q + 1], a2, ni1); } }
;         }
;         sav = (nv[0] + nv[1]) + (nv1[0] + nv1[1]); sai = (ni[0] + ni[1]) + (ni1[0] + ni1[1]);
;         const unsigned cbo = base + (unsigned)s * 512u;
	ds_read_b128 v[148:151], v76 offset:1024
	ds_read_b128 v[152:155], v76 offset:1056
	ds_read_b128 v[156:159], v76 offset:1088
	ds_read_b128 v[160:163], v76 offset:1120
	ds_read_b128 v[164:167], v76 offset:1280
	ds_read_b128 v[168:171], v76 offset:1312
	ds_read_b128 v[172:175], v76 offset:1344
	ds_read_b128 v[176:179], v76 offset:1376
	global_load_ushort v88, v72, s[4:5] offset:0
	global_load_ushort v89, v72, s[0:1] offset:0
	global_load_ushort v90, v72, s[12:13] offset:1024
	global_load_ushort v91, v[74:75], off offset:0
	global_load_ushort v92, v[74:75], off offset:64
	v_mfma_f32_32x32x2_f32 v[0:15], v240, v244, v[0:15]
	v_mfma_f32_32x32x2_f32 v[32:47], v240, v245, v[32:47]
	ds_read_b128 v[192:195], v76 offset:1152
	ds_read_b128 v[196:199], v76 offset:1184
	ds_read_b128 v[200:203], v76 offset:1216
	ds_read_b128 v[204:207], v76 offset:1248
	ds_read_b128 v[208:211], v76 offset:1408
	ds_read_b128 v[212:215], v76 offset:1440
	ds_read_b128 v[216:219], v76 offset:1472
	ds_read_b128 v[220:223], v76 offset:1504
	v_mfma_f32_32x32x2_f32 v[16:31], v241, v244, v[16:31]
	v_mfma_f32_32x32x2_f32 v[48:63], v241, v245, v[48:63]
	s_waitcnt vmcnt(18)
	v_lshlrev_b32_e32 v78, 16, v224
	v_mul_f32_e32 v78, 0xbfb8aa3b, v78
	v_exp_f32_e32 v78, v78
	v_lshlrev_b32_e32 v79, 16, v225
	v_lshlrev_b32_e32 v80, 16, v226
	v_mul_f32_e32 v246, v246, v78
	v_mul_f32_e32 v79, v79, v246
	v_mul_f32_e32 v80, v80, v246
	v_rcp_f32_e32 v248, v246
	s_nop 0
	ds_write2st64_b32 v77, v248, v79 offset0:0 offset1:1
	ds_write_b32 v77, v80 offset:512
	s_waitcnt lgkmcnt(10)
	v_pk_mul_f32 v[64:65], v[0:1], v[148:149]
	v_pk_mul_f32 v[68:69], v[0:1], v[164:165]
	v_pk_fma_f32 v[64:65], v[2:3], v[150:151], v[64:65]
	v_pk_fma_f32 v[68:69], v[2:3], v[166:167], v[68:69]
	v_pk_fma_f32 v[64:65], v[4:5], v[152:153], v[64:65]
	v_pk_fma_f32 v[68:69], v[4:5], v[168:169], v[68:69]
	v_pk_fma_f32 v[64:65], v[6:7], v[154:155], v[64:65]
	v_pk_fma_f32 v[68:69], v[6:7], v[170:171], v[68:69]
	v_pk_fma_f32 v[64:65], v[8:9], v[156:157], v[64:65]
	v_pk_fma_f32 v[68:69], v[8:9], v[172:173], v[68:69]
	v_pk_fma_f32 v[64:65], v[10:11], v[158:159], v[64:65]
	v_pk_fma_f32 v[68:69], v[10:11], v[174:175], v[68:69]
	v_pk_fma_f32 v[64:65], v[12:13], v[160:161], v[64:65]
	v_pk_fma_f32 v[68:69], v[12:13], v[176:177], v[68:69]
	v_pk_fma_f32 v[64:65], v[14:15], v[162:163], v[64:65]
	v_pk_fma_f32 v[68:69], v[14:15], v[178:179], v[68:69]
	v_pk_mul_f32 v[66:67], v[32:33], v[148:149]
	v_pk_mul_f32 v[70:71], v[32:33], v[164:165]
	v_pk_fma_f32 v[66:67], v[34:35], v[150:151], v[66:67]
	v_pk_fma_f32 v[70:71], v[34:35], v[166:167], v[70:71]
	v_pk_fma_f32 v[66:67], v[36:37], v[152:153], v[66:67]
	v_pk_fma_f32 v[70:71], v[36:37], v[168:169], v[70:71]
	v_pk_fma_f32 v[66:67], v[38:39], v[154:155], v[66:67]
	v_pk_fma_f32 v[70:71], v[38:39], v[170:171], v[70:71]
	v_pk_fma_f32 v[66:67], v[40:41], v[156:157], v[66:67]
	v_pk_fma_f32 v[70:71], v[40:41], v[172:173], v[70:71]
	v_pk_fma_f32 v[66:67], v[42:43], v[158:159], v[66:67]
	v_pk_fma_f32 v[70:71], v[42:43], v[174:175], v[70:71]
	v_pk_fma_f32 v[66:67], v[44:45], v[160:161], v[66:67]
	v_pk_fma_f32 v[70:71], v[44:45], v[176:177], v[70:71]
	v_pk_fma_f32 v[66:67], v[46:47], v[162:163], v[66:67]
	v_pk_fma_f32 v[70:71], v[46:47], v[178:179], v[70:71]
	s_waitcnt lgkmcnt(2)
	v_pk_fma_f32 v[64:65], v[16:17], v[192:193], v[64:65]
	v_pk_fma_f32 v[68:69], v[16:17], v[208:209], v[68:69]
	v_pk_fma_f32 v[64:65], v[18:19], v[194:195], v[64:65]
	v_pk_fma_f32 v[68:69], v[18:19], v[210:211], v[68:69]
	v_pk_fma_f32 v[64:65], v[20:21], v[196:197], v[64:65]
	v_pk_fma_f32 v[68:69], v[20:21], v[212:213], v[68:69]
	v_pk_fma_f32 v[64:65], v[22:23], v[198:199], v[64:65]
	v_pk_fma_f32 v[68:69], v[22:23], v[214:215], v[68:69]
	v_pk_fma_f32 v[64:65], v[24:25], v[200:201], v[64:65]
	v_pk_fma_f32 v[68:69], v[24:25], v[216:217], v[68:69]
	v_pk_fma_f32 v[64:65], v[26:27], v[202:203], v[64:65]
	v_pk_fma_f32 v[68:69], v[26:27], v[218:219], v[68:69]
	v_pk_fma_f32 v[64:65], v[28:29], v[204:205], v[64:65]
	v_pk_fma_f32 v[68:69], v[28:29], v[220:221], v[68:69]
	v_pk_fma_f32 v[64:65], v[30:31], v[206:207], v[64:65]
	v_pk_fma_f32 v[68:69], v[30:31], v[222:223], v[68:69]
	v_pk_fma_f32 v[66:67], v[48:49], v[192:193], v[66:67]
	v_pk_fma_f32 v[70:71], v[48:49], v[208:209], v[70:71]
	v_pk_fma_f32 v[66:67], v[50:51], v[194:195], v[66:67]
	v_pk_fma_f32 v[70:71], v[50:51], v[210:211], v[70:71]
	v_pk_fma_f32 v[66:67], v[52:53], v[196:197], v[66:67]
	v_pk_fma_f32 v[70:71], v[52:53], v[212:213], v[70:71]
	v_pk_fma_f32 v[66:67], v[54:55], v[198:199], v[66:67]
	v_pk_fma_f32 v[70:71], v[54:55], v[214:215], v[70:71]
	v_pk_fma_f32 v[66:67], v[56:57], v[200:201], v[66:67]
	v_pk_fma_f32 v[70:71], v[56:57], v[216:217], v[70:71]
	v_pk_fma_f32 v[66:67], v[58:59], v[202:203], v[66:67]
	v_pk_fma_f32 v[70:71], v[58:59], v[218:219], v[70:71]
	v_pk_fma_f32 v[66:67], v[60:61], v[204:205], v[66:67]
	v_pk_fma_f32 v[70:71], v[60:61], v[220:221], v[70:71]
	v_pk_fma_f32 v[66:67], v[62:63], v[206:207], v[66:67]
	v_pk_fma_f32 v[70:71], v[62:63], v[222:223], v[70:71]
	ds_read_b32 v249, v251 offset:0
	ds_read_b32 v250, v251 offset:128
	v_lshlrev_b32_e32 v240, 16, v227
	v_lshlrev_b32_e32 v241, 16, v228
	s_waitcnt lgkmcnt(0)
	v_mul_f32_e32 v240, v240, v249
	v_mul_f32_e32 v241, v241, v250
	v_add_f32_e32 v68, v68, v69
	v_add_f32_e32 v70, v70, v71
	v_add_f32_e32 v64, v64, v65
	v_add_f32_e32 v66, v66, v67
	v_mov_b32_e32 v245, 0
	v_permlane32_swap_b32_e32 v68, v70
	v_permlane32_swap_b32_e32 v64, v66
	v_add_f32_e32 v244, v68, v70
	v_add_f32_e32 v64, v64, v66
	v_bfe_u32 v66, v64, 16, 1
	v_add3_u32 v66, v64, v66, s69
	v_permlane32_swap_b32_e32 v244, v245
	global_store_short_d16_hi v72, v66, s[24:25] offset:-4096
	v_add_u32_e32 v72, 0x400, v72
	v_lshl_add_u64 v[74:75], v[74:75], 0, s[54:55]
	s_branch .Lscan_i_s3e
; template <bool ID> __device__ __forceinline__ void rwkv_scan(const bf16_t* __restrict__ R, const bf16_t* __restrict__ EW, const bf16_t* __restrict__ K, const bf16_t* __restrict__ V, ...
;     ...
;         L[lane] = bf2f(q2[4]); L[64 + lane] = __expf(-bf2f(q1[1])); L[128 + lane] = bf2f(q1[5]); L[192 + lane] = bf2f(q1[2]); L[256 + lane] = bf2f(q1[0]);
;         const float v = bf2f(q1[3]);
; #pragma unroll
;         for (int j = 0; j < 6; ++j) q1[j] = q2[j];
;         { const unsigned o = base + (unsigned)(s + 2 < nsteps ? s + 2 : nsteps - 1) * 512u; q2[0] = R[o]; q2[1] = EW[o]; q2[2] = K[o]; q2[3] = V[o]; q2[4] = A[o]; q2[5] = B[o]; }
;         const f2 sav2 = {sav, sav}, sai2 = {sai, sai}, v2 = {v, v};
;         f2 yv = {0.f, 0.f}, yi = {0.f, 0.f}, yv1 = {0.f, 0.f}, yi1 = {0.f, 0.f}, nv = {0.f, 0.f}, ni = {0.f, 0.f}, nv1 = {0.f, 0.f}, ni1 = {0.f, 0.f};
;         f32x4 ca = pa[0], cw = pa[16], cb = pa[32], ck = pa[48], cr = pa[64];
; #pragma unroll
;         for (int q = 0; q < 16; ++q) {
;             const f32x4 a4 = ca, w4 = cw, b4 = cb, k4 = ck, r4 = cr;
;             if (q < 15) { ca = pa[1 + q]; cw = pa[17 + q]; cb = pa[33 + q]; ck = pa[49 + q]; cr = pa[65 + q]; }
;             __builtin_amdgcn_sched_barrier(0);
;             { const f2 a2 = {a4[0], a4[1]}, w2 = {w4[0], w4[1]}, b2 = {b4[0], b4[1]}, k2 = {k4[0], k4[1]}, r2 = {r4[0], r4[1]};
;               f2 tv = sav2 * b2; tv = pfma(v2, k2, tv); Sv[2 * q] = pfma(Sv[2 * q], w2, tv); yv = pfma(Sv[2 * q], r2, yv); nv = pfma(Sv[2 * q], a2, nv);
;               if (ID) { const f2 ti = sai2 * b2; Si[2 * q] = pfma(Si[2 * q], w2, ti); yi = pfma(Si[2 * q], r2, yi); ni = pfma(Si[2 * q], a2, ni); } }
;             { const f2 a2 = {a4[2], a4[3]}, w2 = {w4[2], w4[3]}, b2 = {b4[2], b4[3]}, k2 = {k4[2], k4[3]}, r2 = {r4[2], r4[3]};
;               f2 tv = sav2 * b2; tv = pfma(v2, k2, tv); Sv[2 * q + 1] = pfma(Sv[2 * q + 1], w2, tv); yv1 = pfma(Sv[2 * q + 1], r2, yv1); nv1 = pfma(Sv[2 * q + 1], a2, nv1);
;               if (ID) { const f2 ti = sai2 * b2; Si[2 * q + 1] = pfma(Si[2 * q + 1], w2, ti); yi1 = pfma(Si[2 * q + 1], r2, yi1); ni1 = pfma(Si[2 * q + 1], a2, ni1); } }
;         }
;         sav = (nv[0] + nv[1]) + (nv1[0] + nv1[1]); sai = (ni[0] + ni[1]) + (ni1[0] + ni1[1]);
;         const unsigned cbo = base + (unsigned)s * 512u;
.Lscan_i_s3x:
	ds_read_b128 v[148:151], v76 offset:1024
	ds_read_b128 v[152:155], v76 offset:1056
	ds_read_b128 v[156:159], v76 offset:1088
	ds_read_b128 v[160:163], v76 offset:1120
	ds_read_b128 v[164:167], v76 offset:1280
	ds_read_b128 v[168:171], v76 offset:1312
	ds_read_b128 v[172:175], v76 offset:1344
	ds_read_b128 v[176:179], v76 offset:1376
	global_load_ushort v88, v72, s[4:5] offset:0
	global_load_ushort v89, v72, s[0:1] offset:0
	global_load_ushort v90, v72, s[12:13] offset:1024
	global_load_ushort v91, v[74:75], off offset:0
	global_load_ushort v92, v[74:75], off offset:64
	v_mfma_f32_32x32x2_f32 v[0:15], v240, v244, v[0:15]
	v_mfma_f32_32x32x2_f32 v[32:47], v240, v245, v[32:47]
	ds_read_b128 v[192:195], v76 offset:1152
	ds_read_b128 v[196:199], v76 offset:1184
	ds_read_b128 v[200:203], v76 offset:1216
	ds_read_b128 v[204:207], v76 offset:1248
	ds_read_b128 v[208:211], v76 offset:1408
	ds_read_b128 v[212:215], v76 offset:1440
	ds_read_b128 v[216:219], v76 offset:1472
	ds_read_b128 v[220:223], v76 offset:1504
	v_mfma_f32_32x32x2_f32 v[16:31], v241, v244, v[16:31]
	v_mfma_f32_32x32x2_f32 v[48:63], v241, v245, v[48:63]
	s_waitcnt vmcnt(18)
	s_waitcnt lgkmcnt(8)
	s_nop 4
	v_pk_mul_f32 v[64:65], v[0:1], v[148:149]
	v_pk_mul_f32 v[68:69], v[0:1], v[164:165]
	v_pk_fma_f32 v[64:65], v[2:3], v[150:151], v[64:65]
	v_pk_fma_f32 v[68:69], v[2:3], v[166:167], v[68:69]
	v_pk_fma_f32 v[64:65], v[4:5], v[152:153], v[64:65]
	v_pk_fma_f32 v[68:69], v[4:5], v[168:169], v[68:69]
	v_pk_fma_f32 v[64:65], v[6:7], v[154:155], v[64:65]
	v_pk_fma_f32 v[68:69], v[6:7], v[170:171], v[68:69]
	v_pk_fma_f32 v[64:65], v[8:9], v[156:157], v[64:65]
	v_pk_fma_f32 v[68:69], v[8:9], v[172:173], v[68:69]
	v_pk_fma_f32 v[64:65], v[10:11], v[158:159], v[64:65]
	v_pk_fma_f32 v[68:69], v[10:11], v[174:175], v[68:69]
	v_pk_fma_f32 v[64:65], v[12:13], v[160:161], v[64:65]
	v_pk_fma_f32 v[68:69], v[12:13], v[176:177], v[68:69]
	v_pk_fma_f32 v[64:65], v[14:15], v[162:163], v[64:65]
	v_pk_fma_f32 v[68:69], v[14:15], v[178:179], v[68:69]
	v_pk_mul_f32 v[66:67], v[32:33], v[148:149]
	v_pk_mul_f32 v[70:71], v[32:33], v[164:165]
	v_pk_fma_f32 v[66:67], v[34:35], v[150:151], v[66:67]
	v_pk_fma_f32 v[70:71], v[34:35], v[166:167], v[70:71]
	v_pk_fma_f32 v[66:67], v[36:37], v[152:153], v[66:67]
	v_pk_fma_f32 v[70:71], v[36:37], v[168:169], v[70:71]
	v_pk_fma_f32 v[66:67], v[38:39], v[154:155], v[66:67]
	v_pk_fma_f32 v[70:71], v[38:39], v[170:171], v[70:71]
	v_pk_fma_f32 v[66:67], v[40:41], v[156:157], v[66:67]
	v_pk_fma_f32 v[70:71], v[40:41], v[172:173], v[70:71]
	v_pk_fma_f32 v[66:67], v[42:43], v[158:159], v[66:67]
	v_pk_fma_f32 v[70:71], v[42:43], v[174:175], v[70:71]
	v_pk_fma_f32 v[66:67], v[44:45], v[160:161], v[66:67]
	v_pk_fma_f32 v[70:71], v[44:45], v[176:177], v[70:71]
	v_pk_fma_f32 v[66:67], v[46:47], v[162:163], v[66:67]
	v_pk_fma_f32 v[70:71], v[46:47], v[178:179], v[70:71]
	s_waitcnt lgkmcnt(0)
	v_pk_fma_f32 v[64:65], v[16:17], v[192:193], v[64:65]
	v_pk_fma_f32 v[68:69], v[16:17], v[208:209], v[68:69]
	v_pk_fma_f32 v[64:65], v[18:19], v[194:195], v[64:65]
	v_pk_fma_f32 v[68:69], v[18:19], v[210:211], v[68:69]
	v_pk_fma_f32 v[64:65], v[20:21], v[196:197], v[64:65]
	v_pk_fma_f32 v[68:69], v[20:21], v[212:213], v[68:69]
	v_pk_fma_f32 v[64:65], v[22:23], v[198:199], v[64:65]
	v_pk_fma_f32 v[68:69], v[22:23], v[214:215], v[68:69]
	v_pk_fma_f32 v[64:65], v[24:25], v[200:201], v[64:65]
	v_pk_fma_f32 v[68:69], v[24:25], v[216:217], v[68:69]
	v_pk_fma_f32 v[64:65], v[26:27], v[202:203], v[64:65]
	v_pk_fma_f32 v[68:69], v[26:27], v[218:219], v[68:69]
	v_pk_fma_f32 v[64:65], v[28:29], v[204:205], v[64:65]
	v_pk_fma_f32 v[68:69], v[28:29], v[220:221], v[68:69]
	v_pk_fma_f32 v[64:65], v[30:31], v[206:207], v[64:65]
	v_pk_fma_f32 v[68:69], v[30:31], v[222:223], v[68:69]
	v_pk_fma_f32 v[66:67], v[48:49], v[192:193], v[66:67]
	v_pk_fma_f32 v[70:71], v[48:49], v[208:209], v[70:71]
	v_pk_fma_f32 v[66:67], v[50:51], v[194:195], v[66:67]
	v_pk_fma_f32 v[70:71], v[50:51], v[210:211], v[70:71]
	v_pk_fma_f32 v[66:67], v[52:53], v[196:197], v[66:67]
	v_pk_fma_f32 v[70:71], v[52:53], v[212:213], v[70:71]
	v_pk_fma_f32 v[66:67], v[54:55], v[198:199], v[66:67]
	v_pk_fma_f32 v[70:71], v[54:55], v[214:215], v[70:71]
	v_pk_fma_f32 v[66:67], v[56:57], v[200:201], v[66:67]
	v_pk_fma_f32 v[70:71], v[56:57], v[216:217], v[70:71]
	v_pk_fma_f32 v[66:67], v[58:59], v[202:203], v[66:67]
	v_pk_fma_f32 v[70:71], v[58:59], v[218:219], v[70:71]
	v_pk_fma_f32 v[66:67], v[60:61], v[204:205], v[66:67]
	v_pk_fma_f32 v[70:71], v[60:61], v[220:221], v[70:71]
	v_pk_fma_f32 v[66:67], v[62:63], v[206:207], v[66:67]
	v_pk_fma_f32 v[70:71], v[62:63], v[222:223], v[70:71]
	v_add_f32_e32 v68, v68, v69
	v_add_f32_e32 v70, v70, v71
	v_add_f32_e32 v64, v64, v65
	v_add_f32_e32 v66, v66, v67
	v_mov_b32_e32 v245, 0
	v_permlane32_swap_b32_e32 v68, v70
	v_permlane32_swap_b32_e32 v64, v66
	v_add_f32_e32 v244, v68, v70
	v_add_f32_e32 v64, v64, v66
	v_bfe_u32 v66, v64, 16, 1
	v_add3_u32 v66, v64, v66, s69
	v_permlane32_swap_b32_e32 v244, v245
	global_store_short_d16_hi v72, v66, s[24:25] offset:-4096
	ds_write_b32 v77, v246 offset:0
	ds_read_b128 v[148:151], v76 offset:0
	ds_read_b128 v[152:155], v76 offset:32
	ds_read_b128 v[156:159], v76 offset:64
	ds_read_b128 v[160:163], v76 offset:96
	ds_read_b128 v[164:167], v76 offset:128
	ds_read_b128 v[168:171], v76 offset:160
	ds_read_b128 v[172:175], v76 offset:192
	ds_read_b128 v[176:179], v76 offset:224
	s_waitcnt lgkmcnt(0)
; __device__ __forceinline__ f2 pfma(f2 a, f2 b, f2 c) { return __builtin_elementwise_fma(a, b, c); }
; template <bool ID> __device__ __forceinline__ void rwkv_scan(const bf16_t* __restrict__ R, const bf16_t* __restrict__ EW, const bf16_t* __restrict__ K, const bf16_t* __restrict__ V, ...
;     ...
;               f2 tv = sav2 * b2; tv = pfma(v2, k2, tv); Sv[2 * q] = pfma(Sv[2 * q], w2, tv); yv = pfma(Sv[2 * q], r2, yv); nv = pfma(Sv[2 * q], a2, nv);
;               if (ID) { const f2 ti = sai2 * b2; Si[2 * q] = pfma(Si[2 * q], w2, ti); yi = pfma(Si[2 * q], r2, yi); ni = pfma(Si[2 * q], a2, ni); } }
; __device__ void phase_rwkv_scan(const Ctx& p, int l, LAS unsigned char* lds) {
;     ...
;             float* pp = P + (size_t)item2 * 4096 + ln * 64; float* up = UC + (size_t)item2 * 4096 + ln * 64;
; #pragma unroll
;             for (int i = 0; i < 32; i += 2) { *(float4*)(pp + 2 * i) = make_float4(Si[i][0], Si[i][1], Si[i + 1][0], Si[i + 1][1]); *(float4*)(up + 2 * i) = make_float4(Sv[i][0], Sv[i][1], Sv[i + 1][0], Sv[i + 1][1]); }
	v_pk_mul_f32 v[0:1], v[0:1], v[148:149]
	v_pk_mul_f32 v[2:3], v[2:3], v[150:151]
	v_pk_mul_f32 v[4:5], v[4:5], v[152:153]
	v_pk_mul_f32 v[6:7], v[6:7], v[154:155]
	v_pk_mul_f32 v[8:9], v[8:9], v[156:157]
	v_pk_mul_f32 v[10:11], v[10:11], v[158:159]
	v_pk_mul_f32 v[12:13], v[12:13], v[160:161]
	v_pk_mul_f32 v[14:15], v[14:15], v[162:163]
	v_pk_mul_f32 v[16:17], v[16:17], v[164:165]
	v_pk_mul_f32 v[18:19], v[18:19], v[166:167]
	v_pk_mul_f32 v[20:21], v[20:21], v[168:169]
	v_pk_mul_f32 v[22:23], v[22:23], v[170:171]
	v_pk_mul_f32 v[24:25], v[24:25], v[172:173]
	v_pk_mul_f32 v[26:27], v[26:27], v[174:175]
	v_pk_mul_f32 v[28:29], v[28:29], v[176:177]
	v_pk_mul_f32 v[30:31], v[30:31], v[178:179]
	v_pk_mul_f32 v[32:33], v[32:33], v[148:149]
	v_pk_mul_f32 v[34:35], v[34:35], v[150:151]
	v_pk_mul_f32 v[36:37], v[36:37], v[152:153]
	v_pk_mul_f32 v[38:39], v[38:39], v[154:155]
	v_pk_mul_f32 v[40:41], v[40:41], v[156:157]
	v_pk_mul_f32 v[42:43], v[42:43], v[158:159]
	v_pk_mul_f32 v[44:45], v[44:45], v[160:161]
	v_pk_mul_f32 v[46:47], v[46:47], v[162:163]
	v_pk_mul_f32 v[48:49], v[48:49], v[164:165]
	v_pk_mul_f32 v[50:51], v[50:51], v[166:167]
	v_pk_mul_f32 v[52:53], v[52:53], v[168:169]
	v_pk_mul_f32 v[54:55], v[54:55], v[170:171]
	v_pk_mul_f32 v[56:57], v[56:57], v[172:173]
	v_pk_mul_f32 v[58:59], v[58:59], v[174:175]
	v_pk_mul_f32 v[60:61], v[60:61], v[176:177]
	v_pk_mul_f32 v[62:63], v[62:63], v[178:179]
	v_mov_b32_e32 v246, 1.0
	v_lshlrev_b32_e32 v78, 16, v224
	v_mul_f32_e32 v78, 0xbfb8aa3b, v78
	v_exp_f32_e32 v78, v78
	v_lshlrev_b32_e32 v79, 16, v225
	v_lshlrev_b32_e32 v80, 16, v226
	v_mul_f32_e32 v246, v246, v78
	v_mul_f32_e32 v79, v79, v246
	v_mul_f32_e32 v80, v80, v246
	v_rcp_f32_e32 v248, v246
	s_nop 0
	ds_write2st64_b32 v77, v248, v79 offset0:0 offset1:1
	ds_write_b32 v77, v80 offset:512
	ds_read_b32 v249, v251 offset:0
	ds_read_b32 v250, v251 offset:128
	v_lshlrev_b32_e32 v240, 16, v227
	v_lshlrev_b32_e32 v241, 16, v228
	s_waitcnt lgkmcnt(0)
	v_mul_f32_e32 v240, v240, v249
	v_mul_f32_e32 v241, v241, v250
	s_waitcnt lgkmcnt(0)
	v_add_u32_e32 v72, 0x400, v72
	v_lshl_add_u64 v[74:75], v[74:75], 0, s[54:55]
.Lscan_i_s3e:
	s_add_i32 s41, s41, 1
	s_cmpk_lg_i32 s41, 32
	s_cbranch_scc1 .Lscan_i_loop
	s_waitcnt vmcnt(0) lgkmcnt(0)
	s_ashr_i32 s15, s36, 31
	s_mov_b32 s14, s36
	s_lshl_b64 s[14:15], s[14:15], 14
	s_add_u32 s14, s37, s14
	s_addc_u32 s15, s38, s15
	v_and_b32_e32 v79, 31, v139
	v_lshrrev_b32_e32 v78, 5, v139
	v_lshlrev_b32_e32 v79, 8, v79
	v_lshl_add_u32 v79, v78, 4, v79
	v_add_u32_e32 v80, 0x2000, v79
	global_store_dwordx4 v79, v[0:3], s[14:15] offset:0
	global_store_dwordx4 v79, v[4:7], s[14:15] offset:32
	global_store_dwordx4 v79, v[8:11], s[14:15] offset:64
	global_store_dwordx4 v79, v[12:15], s[14:15] offset:96
	global_store_dwordx4 v79, v[16:19], s[14:15] offset:128
	global_store_dwordx4 v79, v[20:23], s[14:15] offset:160
	global_store_dwordx4 v79, v[24:27], s[14:15] offset:192
	global_store_dwordx4 v79, v[28:31], s[14:15] offset:224
	global_store_dwordx4 v80, v[32:35], s[14:15] offset:0
	global_store_dwordx4 v80, v[36:39], s[14:15] offset:32
	global_store_dwordx4 v80, v[40:43], s[14:15] offset:64
	global_store_dwordx4 v80, v[44:47], s[14:15] offset:96
	global_store_dwordx4 v80, v[48:51], s[14:15] offset:128
	global_store_dwordx4 v80, v[52:55], s[14:15] offset:160
	global_store_dwordx4 v80, v[56:59], s[14:15] offset:192
	global_store_dwordx4 v80, v[60:63], s[14:15] offset:224
	s_branch .Lscan_tail
